# in-proj: specialised straight-line epilogues for gla q/k, silu gate and sigmoid merge column tiles (same math); first grid sync via counter barrier
# speedup vs baseline: 1.0149x; 1.0119x over previous
.LBB0_46:
	v_bfe_u32 v142, v0, 10, 10
	v_bfe_u32 v143, v0, 20, 10
	v_or3_b32 v0, v148, v142, v143
	v_cmp_eq_u32_e32 vcc, 0, v0
	s_waitcnt vmcnt(0)
	s_waitcnt vmcnt(0)
	s_barrier
	s_and_saveexec_b64 s[0:1], vcc
	s_cbranch_execz .LBB0_56
	buffer_wbl2 sc1
	s_waitcnt vmcnt(0)
	s_add_u32 s4, s54, 0x322c080
	s_addc_u32 s5, s55, 0
	v_mov_b32_e32 v0, 0
	v_mov_b32_e32 v1, 1
	global_atomic_add v0, v1, s[4:5]
.Lgs0_poll:
	global_load_dword v1, v0, s[4:5] sc1
	s_waitcnt vmcnt(0)
	v_cmp_gt_u32_e32 vcc, s50, v1
	s_cbranch_vccz .Lgs0_done
	s_sleep 8
	s_branch .Lgs0_poll

.LBB0_82:
	s_or_b64 exec, exec, s[4:5]
	s_add_u32 s78, s54, 0x322c000
	s_addc_u32 s79, s55, 0
	s_waitcnt vmcnt(0)
	s_barrier
	v_cmp_eq_u32_e64 s[4:5], 0, v148
	s_mov_b64 s[0:1], exec
	s_nop 0
	v_writelane_b32 v255, s4, 19
	s_nop 1
	v_writelane_b32 v255, s5, 20
	s_and_b64 s[4:5], s[0:1], s[4:5]
	s_mov_b64 exec, s[4:5]
	s_cbranch_execz .LBB0_88
	s_mov_b64 s[6:7], exec
	v_mbcnt_lo_u32_b32 v0, s6, 0
	v_mbcnt_hi_u32_b32 v0, s7, v0
	v_cmp_eq_u32_e32 vcc, 0, v0
	buffer_wbl2 sc1
	s_waitcnt vmcnt(0)
	buffer_inv sc1
	s_and_saveexec_b64 s[4:5], vcc
	s_cbranch_execz .LBB0_85
	s_bcnt1_i32_b64 s3, s[6:7]
	v_mov_b32_e32 v0, 0
	v_mov_b32_e32 v1, s3
	global_atomic_add v0, v1, s[78:79]

.LBB0_86:
	s_sleep 16
	global_load_dword v1, v0, s[78:79] sc1
	s_waitcnt vmcnt(0)
	v_cmp_gt_u32_e32 vcc, s50, v1
	s_cbranch_vccnz .LBB0_86
.LBB0_87:
	buffer_inv sc1
.LBB0_88:
	s_or_b64 exec, exec, s[0:1]
	v_lshl_add_u64 v[0:1], v[148:149], 4, s[54:55]
	s_mov_b64 s[0:1], 0x29e0000
	v_mov_b32_e32 v2, 0x20000
	v_lshl_add_u64 v[0:1], v[0:1], 0, s[0:1]
	v_lshl_or_b32 v2, v148, 4, v2
	s_mov_b64 s[0:1], 0
	s_mov_b64 s[4:5], 0x2000
	v_mov_b32_e32 v3, v254
	s_barrier

.LBB0_117:
	s_or_b64 exec, exec, s[0:1]
	s_cmpk_lt_u32 s96, 0xc00
	s_cbranch_scc1 .Lipe_old
	s_cmpk_lt_u32 s96, 0x1000
	s_cbranch_scc1 .Lipe_gqk
	s_cmpk_lt_u32 s96, 0x1400
	s_cbranch_scc1 .Lipe_old
	s_cmpk_lt_u32 s96, 0x1800
	s_cbranch_scc1 .Lipe_sg
	s_cmpk_lt_u32 s96, 0x2000
	s_cbranch_scc1 .Lipe_mg
	s_branch .Lipe_old
.Lipe_gqk:
	s_lshl_b32 s8, s4, 10
	s_cmpk_lt_u32 s96, 0xe00
	s_mov_b32 s9, 0x28c00000
	s_cselect_b32 s9, 0x24c00000, s9
	s_cselect_b32 s10, 0x3db504f3, 1.0
	s_movk_i32 s11, 0xe00
	s_cselect_b32 s11, 0xc00, s11
	s_sub_u32 s11, s96, s11
	s_lshl_b32 s11, s11, 1
	s_add_u32 s8, s8, s11
	s_add_u32 s6, s54, s9
	s_addc_u32 s7, s55, 0
	s_add_u32 s6, s6, s8
	s_addc_u32 s7, s7, 0
	v_and_b32_e32 v158, 63, v148
	v_lshrrev_b32_e32 v159, 6, v148
	v_lshrrev_b32_e32 v160, 2, v159
	v_and_b32_e32 v159, 3, v159
	v_and_b32_e32 v161, 15, v158
	v_lshrrev_b32_e32 v158, 4, v158
	v_lshl_add_u32 v160, v160, 6, v161
	v_mul_u32_u24_e32 v155, 0x110, v160
	v_lshlrev_b32_e32 v159, 6, v159
	v_lshl_add_u32 v159, v158, 3, v159
	v_add_u32_e32 v155, v155, v159
	v_lshrrev_b32_e32 v158, 4, v148
	v_and_b32_e32 v159, 15, v148
	v_mul_u32_u24_e32 v156, 0x110, v158
	v_lshl_add_u32 v156, v159, 4, v156
	v_lshlrev_b32_e32 v157, 10, v158
	v_lshl_add_u32 v157, v159, 4, v157
	v_mul_f32_e32 v132, s10, v124
	v_mul_f32_e32 v133, s10, v125
	v_mul_f32_e32 v134, s10, v126
	v_mul_f32_e32 v135, s10, v127
	v_cvt_pk_bf16_f32 v136, v132, v133
	v_cvt_pk_bf16_f32 v137, v134, v135
	ds_write_b64 v155, v[136:137] offset:0
	v_mul_f32_e32 v132, s10, v120
	v_mul_f32_e32 v133, s10, v121
	v_mul_f32_e32 v134, s10, v122
	v_mul_f32_e32 v135, s10, v123
	v_cvt_pk_bf16_f32 v138, v132, v133
	v_cvt_pk_bf16_f32 v139, v134, v135
	ds_write_b64 v155, v[138:139] offset:32
	v_mul_f32_e32 v132, s10, v116
	v_mul_f32_e32 v133, s10, v117
	v_mul_f32_e32 v134, s10, v118
	v_mul_f32_e32 v135, s10, v119
	v_cvt_pk_bf16_f32 v136, v132, v133
	v_cvt_pk_bf16_f32 v137, v134, v135
	ds_write_b64 v155, v[136:137] offset:4352
	v_mul_f32_e32 v132, s10, v112
	v_mul_f32_e32 v133, s10, v113
	v_mul_f32_e32 v134, s10, v114
	v_mul_f32_e32 v135, s10, v115
	v_cvt_pk_bf16_f32 v138, v132, v133
	v_cvt_pk_bf16_f32 v139, v134, v135
	ds_write_b64 v155, v[138:139] offset:4384
	v_mul_f32_e32 v132, s10, v108
	v_mul_f32_e32 v133, s10, v109
	v_mul_f32_e32 v134, s10, v110
	v_mul_f32_e32 v135, s10, v111
	v_cvt_pk_bf16_f32 v136, v132, v133
	v_cvt_pk_bf16_f32 v137, v134, v135
	ds_write_b64 v155, v[136:137] offset:8704
	v_mul_f32_e32 v132, s10, v104
	v_mul_f32_e32 v133, s10, v105
	v_mul_f32_e32 v134, s10, v106
	v_mul_f32_e32 v135, s10, v107
	v_cvt_pk_bf16_f32 v138, v132, v133
	v_cvt_pk_bf16_f32 v139, v134, v135
	ds_write_b64 v155, v[138:139] offset:8736
	v_mul_f32_e32 v132, s10, v100
	v_mul_f32_e32 v133, s10, v101
	v_mul_f32_e32 v134, s10, v102
	v_mul_f32_e32 v135, s10, v103
	v_cvt_pk_bf16_f32 v136, v132, v133
	v_cvt_pk_bf16_f32 v137, v134, v135
	ds_write_b64 v155, v[136:137] offset:13056
	v_mul_f32_e32 v132, s10, v96
	v_mul_f32_e32 v133, s10, v97
	v_mul_f32_e32 v134, s10, v98
	v_mul_f32_e32 v135, s10, v99
	v_cvt_pk_bf16_f32 v138, v132, v133
	v_cvt_pk_bf16_f32 v139, v134, v135
	ds_write_b64 v155, v[138:139] offset:13088
	s_waitcnt lgkmcnt(0)
	s_barrier
	ds_read_b128 v[132:135], v156 offset:0
	ds_read_b128 v[136:139], v156 offset:8704
	s_add_u32 s8, s6, 0x0
	s_addc_u32 s9, s7, 0
	s_waitcnt lgkmcnt(1)
	global_store_dwordx4 v157, v[132:135], s[8:9] sc1
	s_add_u32 s8, s6, 0x8000
	s_addc_u32 s9, s7, 0
	s_waitcnt lgkmcnt(0)
	global_store_dwordx4 v157, v[136:139], s[8:9] sc1
	ds_read_b128 v[132:135], v156 offset:17408
	ds_read_b128 v[136:139], v156 offset:26112
	s_add_u32 s8, s6, 0x10000
	s_addc_u32 s9, s7, 0
	s_waitcnt lgkmcnt(1)
	global_store_dwordx4 v157, v[132:135], s[8:9] sc1
	s_add_u32 s8, s6, 0x18000
	s_addc_u32 s9, s7, 0
	s_waitcnt lgkmcnt(0)
	global_store_dwordx4 v157, v[136:139], s[8:9] sc1
	s_barrier
	v_mul_f32_e32 v132, s10, v92
	v_mul_f32_e32 v133, s10, v93
	v_mul_f32_e32 v134, s10, v94
	v_mul_f32_e32 v135, s10, v95
	v_cvt_pk_bf16_f32 v136, v132, v133
	v_cvt_pk_bf16_f32 v137, v134, v135
	ds_write_b64 v155, v[136:137] offset:0
	v_mul_f32_e32 v132, s10, v88
	v_mul_f32_e32 v133, s10, v89
	v_mul_f32_e32 v134, s10, v90
	v_mul_f32_e32 v135, s10, v91
	v_cvt_pk_bf16_f32 v138, v132, v133
	v_cvt_pk_bf16_f32 v139, v134, v135
	ds_write_b64 v155, v[138:139] offset:32
	v_mul_f32_e32 v132, s10, v84
	v_mul_f32_e32 v133, s10, v85
	v_mul_f32_e32 v134, s10, v86
	v_mul_f32_e32 v135, s10, v87
	v_cvt_pk_bf16_f32 v136, v132, v133
	v_cvt_pk_bf16_f32 v137, v134, v135
	ds_write_b64 v155, v[136:137] offset:4352
	v_mul_f32_e32 v132, s10, v80
	v_mul_f32_e32 v133, s10, v81
	v_mul_f32_e32 v134, s10, v82
	v_mul_f32_e32 v135, s10, v83
	v_cvt_pk_bf16_f32 v138, v132, v133
	v_cvt_pk_bf16_f32 v139, v134, v135
	ds_write_b64 v155, v[138:139] offset:4384
	v_mul_f32_e32 v132, s10, v76
	v_mul_f32_e32 v133, s10, v77
	v_mul_f32_e32 v134, s10, v78
	v_mul_f32_e32 v135, s10, v79
	v_cvt_pk_bf16_f32 v136, v132, v133
	v_cvt_pk_bf16_f32 v137, v134, v135
	ds_write_b64 v155, v[136:137] offset:8704
	v_mul_f32_e32 v132, s10, v72
	v_mul_f32_e32 v133, s10, v73
	v_mul_f32_e32 v134, s10, v74
	v_mul_f32_e32 v135, s10, v75
	v_cvt_pk_bf16_f32 v138, v132, v133
	v_cvt_pk_bf16_f32 v139, v134, v135
	ds_write_b64 v155, v[138:139] offset:8736
	v_mul_f32_e32 v132, s10, v68
	v_mul_f32_e32 v133, s10, v69
	v_mul_f32_e32 v134, s10, v70
	v_mul_f32_e32 v135, s10, v71
	v_cvt_pk_bf16_f32 v136, v132, v133
	v_cvt_pk_bf16_f32 v137, v134, v135
	ds_write_b64 v155, v[136:137] offset:13056
	v_mul_f32_e32 v132, s10, v64
	v_mul_f32_e32 v133, s10, v65
	v_mul_f32_e32 v134, s10, v66
	v_mul_f32_e32 v135, s10, v67
	v_cvt_pk_bf16_f32 v138, v132, v133
	v_cvt_pk_bf16_f32 v139, v134, v135
	ds_write_b64 v155, v[138:139] offset:13088
	s_waitcnt lgkmcnt(0)
	s_barrier
	ds_read_b128 v[132:135], v156 offset:0
	ds_read_b128 v[136:139], v156 offset:8704
	s_add_u32 s8, s6, 0x100
	s_addc_u32 s9, s7, 0
	s_waitcnt lgkmcnt(1)
	global_store_dwordx4 v157, v[132:135], s[8:9] sc1
	s_add_u32 s8, s6, 0x8100
	s_addc_u32 s9, s7, 0
	s_waitcnt lgkmcnt(0)
	global_store_dwordx4 v157, v[136:139], s[8:9] sc1
	ds_read_b128 v[132:135], v156 offset:17408
	ds_read_b128 v[136:139], v156 offset:26112
	s_add_u32 s8, s6, 0x10100
	s_addc_u32 s9, s7, 0
	s_waitcnt lgkmcnt(1)
	global_store_dwordx4 v157, v[132:135], s[8:9] sc1
	s_add_u32 s8, s6, 0x18100
	s_addc_u32 s9, s7, 0
	s_waitcnt lgkmcnt(0)
	global_store_dwordx4 v157, v[136:139], s[8:9] sc1
	s_barrier
	v_mul_f32_e32 v132, s10, v60
	v_mul_f32_e32 v133, s10, v61
	v_mul_f32_e32 v134, s10, v62
	v_mul_f32_e32 v135, s10, v63
	v_cvt_pk_bf16_f32 v136, v132, v133
	v_cvt_pk_bf16_f32 v137, v134, v135
	ds_write_b64 v155, v[136:137] offset:0
	v_mul_f32_e32 v132, s10, v56
	v_mul_f32_e32 v133, s10, v57
	v_mul_f32_e32 v134, s10, v58
	v_mul_f32_e32 v135, s10, v59
	v_cvt_pk_bf16_f32 v138, v132, v133
	v_cvt_pk_bf16_f32 v139, v134, v135
	ds_write_b64 v155, v[138:139] offset:32
	v_mul_f32_e32 v132, s10, v52
	v_mul_f32_e32 v133, s10, v53
	v_mul_f32_e32 v134, s10, v54
	v_mul_f32_e32 v135, s10, v55
	v_cvt_pk_bf16_f32 v136, v132, v133
	v_cvt_pk_bf16_f32 v137, v134, v135
	ds_write_b64 v155, v[136:137] offset:4352
	v_mul_f32_e32 v132, s10, v48
	v_mul_f32_e32 v133, s10, v49
	v_mul_f32_e32 v134, s10, v50
	v_mul_f32_e32 v135, s10, v51
	v_cvt_pk_bf16_f32 v138, v132, v133
	v_cvt_pk_bf16_f32 v139, v134, v135
	ds_write_b64 v155, v[138:139] offset:4384
	v_mul_f32_e32 v132, s10, v44
	v_mul_f32_e32 v133, s10, v45
	v_mul_f32_e32 v134, s10, v46
	v_mul_f32_e32 v135, s10, v47
	v_cvt_pk_bf16_f32 v136, v132, v133
	v_cvt_pk_bf16_f32 v137, v134, v135
	ds_write_b64 v155, v[136:137] offset:8704
	v_mul_f32_e32 v132, s10, v40
	v_mul_f32_e32 v133, s10, v41
	v_mul_f32_e32 v134, s10, v42
	v_mul_f32_e32 v135, s10, v43
	v_cvt_pk_bf16_f32 v138, v132, v133
	v_cvt_pk_bf16_f32 v139, v134, v135
	ds_write_b64 v155, v[138:139] offset:8736
	v_mul_f32_e32 v132, s10, v36
	v_mul_f32_e32 v133, s10, v37
	v_mul_f32_e32 v134, s10, v38
	v_mul_f32_e32 v135, s10, v39
	v_cvt_pk_bf16_f32 v136, v132, v133
	v_cvt_pk_bf16_f32 v137, v134, v135
	ds_write_b64 v155, v[136:137] offset:13056
	v_mul_f32_e32 v132, s10, v32
	v_mul_f32_e32 v133, s10, v33
	v_mul_f32_e32 v134, s10, v34
	v_mul_f32_e32 v135, s10, v35
	v_cvt_pk_bf16_f32 v138, v132, v133
	v_cvt_pk_bf16_f32 v139, v134, v135
	ds_write_b64 v155, v[138:139] offset:13088
	s_waitcnt lgkmcnt(0)
	s_barrier
	ds_read_b128 v[132:135], v156 offset:0
	ds_read_b128 v[136:139], v156 offset:8704
	s_add_u32 s8, s6, 0x20000
	s_addc_u32 s9, s7, 0
	s_waitcnt lgkmcnt(1)
	global_store_dwordx4 v157, v[132:135], s[8:9] sc1
	s_add_u32 s8, s6, 0x28000
	s_addc_u32 s9, s7, 0
	s_waitcnt lgkmcnt(0)
	global_store_dwordx4 v157, v[136:139], s[8:9] sc1
	ds_read_b128 v[132:135], v156 offset:17408
	ds_read_b128 v[136:139], v156 offset:26112
	s_add_u32 s8, s6, 0x30000
	s_addc_u32 s9, s7, 0
	s_waitcnt lgkmcnt(1)
	global_store_dwordx4 v157, v[132:135], s[8:9] sc1
	s_add_u32 s8, s6, 0x38000
	s_addc_u32 s9, s7, 0
	s_waitcnt lgkmcnt(0)
	global_store_dwordx4 v157, v[136:139], s[8:9] sc1
	s_barrier
	v_mul_f32_e32 v132, s10, v28
	v_mul_f32_e32 v133, s10, v29
	v_mul_f32_e32 v134, s10, v30
	v_mul_f32_e32 v135, s10, v31
	v_cvt_pk_bf16_f32 v136, v132, v133
	v_cvt_pk_bf16_f32 v137, v134, v135
	ds_write_b64 v155, v[136:137] offset:0
	v_mul_f32_e32 v132, s10, v24
	v_mul_f32_e32 v133, s10, v25
	v_mul_f32_e32 v134, s10, v26
	v_mul_f32_e32 v135, s10, v27
	v_cvt_pk_bf16_f32 v138, v132, v133
	v_cvt_pk_bf16_f32 v139, v134, v135
	ds_write_b64 v155, v[138:139] offset:32
	v_mul_f32_e32 v132, s10, v20
	v_mul_f32_e32 v133, s10, v21
	v_mul_f32_e32 v134, s10, v22
	v_mul_f32_e32 v135, s10, v23
	v_cvt_pk_bf16_f32 v136, v132, v133
	v_cvt_pk_bf16_f32 v137, v134, v135
	ds_write_b64 v155, v[136:137] offset:4352
	v_mul_f32_e32 v132, s10, v16
	v_mul_f32_e32 v133, s10, v17
	v_mul_f32_e32 v134, s10, v18
	v_mul_f32_e32 v135, s10, v19
	v_cvt_pk_bf16_f32 v138, v132, v133
	v_cvt_pk_bf16_f32 v139, v134, v135
	ds_write_b64 v155, v[138:139] offset:4384
	v_mul_f32_e32 v132, s10, v12
	v_mul_f32_e32 v133, s10, v13
	v_mul_f32_e32 v134, s10, v14
	v_mul_f32_e32 v135, s10, v15
	v_cvt_pk_bf16_f32 v136, v132, v133
	v_cvt_pk_bf16_f32 v137, v134, v135
	ds_write_b64 v155, v[136:137] offset:8704
	v_mul_f32_e32 v132, s10, v8
	v_mul_f32_e32 v133, s10, v9
	v_mul_f32_e32 v134, s10, v10
	v_mul_f32_e32 v135, s10, v11
	v_cvt_pk_bf16_f32 v138, v132, v133
	v_cvt_pk_bf16_f32 v139, v134, v135
	ds_write_b64 v155, v[138:139] offset:8736
	v_mul_f32_e32 v132, s10, v4
	v_mul_f32_e32 v133, s10, v5
	v_mul_f32_e32 v134, s10, v6
	v_mul_f32_e32 v135, s10, v7
	v_cvt_pk_bf16_f32 v136, v132, v133
	v_cvt_pk_bf16_f32 v137, v134, v135
	ds_write_b64 v155, v[136:137] offset:13056
	v_mul_f32_e32 v132, s10, v0
	v_mul_f32_e32 v133, s10, v1
	v_mul_f32_e32 v134, s10, v2
	v_mul_f32_e32 v135, s10, v3
	v_cvt_pk_bf16_f32 v138, v132, v133
	v_cvt_pk_bf16_f32 v139, v134, v135
	ds_write_b64 v155, v[138:139] offset:13088
	s_waitcnt lgkmcnt(0)
	s_barrier
	ds_read_b128 v[132:135], v156 offset:0
	ds_read_b128 v[136:139], v156 offset:8704
	s_add_u32 s8, s6, 0x20100
	s_addc_u32 s9, s7, 0
	s_waitcnt lgkmcnt(1)
	global_store_dwordx4 v157, v[132:135], s[8:9] sc1
	s_add_u32 s8, s6, 0x28100
	s_addc_u32 s9, s7, 0
	s_waitcnt lgkmcnt(0)
	global_store_dwordx4 v157, v[136:139], s[8:9] sc1
	ds_read_b128 v[132:135], v156 offset:17408
	ds_read_b128 v[136:139], v156 offset:26112
	s_add_u32 s8, s6, 0x30100
	s_addc_u32 s9, s7, 0
	s_waitcnt lgkmcnt(1)
	global_store_dwordx4 v157, v[132:135], s[8:9] sc1
	s_add_u32 s8, s6, 0x38100
	s_addc_u32 s9, s7, 0
	s_waitcnt lgkmcnt(0)
	global_store_dwordx4 v157, v[136:139], s[8:9] sc1
	s_barrier
	s_branch .LBB0_93
.Lipe_sg:
	s_lshl_b32 s8, s4, 11
	s_sub_u32 s11, s96, 0x1400
	s_lshl_b32 s11, s11, 1
	s_add_u32 s8, s8, s11
	s_add_u32 s6, s54, 0x35200000
	s_addc_u32 s7, s55, 0
	s_add_u32 s6, s6, s8
	s_addc_u32 s7, s7, 0
	v_and_b32_e32 v158, 63, v148
	v_lshrrev_b32_e32 v159, 6, v148
	v_lshrrev_b32_e32 v160, 2, v159
	v_and_b32_e32 v159, 3, v159
	v_and_b32_e32 v161, 15, v158
	v_lshrrev_b32_e32 v158, 4, v158
	v_lshl_add_u32 v160, v160, 6, v161
	v_mul_u32_u24_e32 v155, 0x110, v160
	v_lshlrev_b32_e32 v159, 6, v159
	v_lshl_add_u32 v159, v158, 3, v159
	v_add_u32_e32 v155, v155, v159
	v_lshrrev_b32_e32 v158, 4, v148
	v_and_b32_e32 v159, 15, v148
	v_mul_u32_u24_e32 v156, 0x110, v158
	v_lshl_add_u32 v156, v159, 4, v156
	v_lshlrev_b32_e32 v157, 11, v158
	v_lshl_add_u32 v157, v159, 4, v157
	v_mul_f32_e32 v132, 0xbfb8aa3b, v124
	v_mul_f32_e32 v133, 0xbfb8aa3b, v125
	v_mul_f32_e32 v134, 0xbfb8aa3b, v126
	v_mul_f32_e32 v135, 0xbfb8aa3b, v127
	v_exp_f32_e32 v132, v132
	v_exp_f32_e32 v133, v133
	v_exp_f32_e32 v134, v134
	v_exp_f32_e32 v135, v135
	v_add_f32_e32 v132, 1.0, v132
	v_add_f32_e32 v133, 1.0, v133
	v_add_f32_e32 v134, 1.0, v134
	v_add_f32_e32 v135, 1.0, v135
	v_rcp_f32_e32 v132, v132
	v_rcp_f32_e32 v133, v133
	v_rcp_f32_e32 v134, v134
	v_rcp_f32_e32 v135, v135
	v_mul_f32_e32 v132, v124, v132
	v_mul_f32_e32 v133, v125, v133
	v_mul_f32_e32 v134, v126, v134
	v_mul_f32_e32 v135, v127, v135
	v_cvt_pk_bf16_f32 v136, v132, v133
	v_cvt_pk_bf16_f32 v137, v134, v135
	ds_write_b64 v155, v[136:137] offset:0
	v_mul_f32_e32 v132, 0xbfb8aa3b, v120
	v_mul_f32_e32 v133, 0xbfb8aa3b, v121
	v_mul_f32_e32 v134, 0xbfb8aa3b, v122
	v_mul_f32_e32 v135, 0xbfb8aa3b, v123
	v_exp_f32_e32 v132, v132
	v_exp_f32_e32 v133, v133
	v_exp_f32_e32 v134, v134
	v_exp_f32_e32 v135, v135
	v_add_f32_e32 v132, 1.0, v132
	v_add_f32_e32 v133, 1.0, v133
	v_add_f32_e32 v134, 1.0, v134
	v_add_f32_e32 v135, 1.0, v135
	v_rcp_f32_e32 v132, v132
	v_rcp_f32_e32 v133, v133
	v_rcp_f32_e32 v134, v134
	v_rcp_f32_e32 v135, v135
	v_mul_f32_e32 v132, v120, v132
	v_mul_f32_e32 v133, v121, v133
	v_mul_f32_e32 v134, v122, v134
	v_mul_f32_e32 v135, v123, v135
	v_cvt_pk_bf16_f32 v138, v132, v133
	v_cvt_pk_bf16_f32 v139, v134, v135
	ds_write_b64 v155, v[138:139] offset:32
	v_mul_f32_e32 v132, 0xbfb8aa3b, v116
	v_mul_f32_e32 v133, 0xbfb8aa3b, v117
	v_mul_f32_e32 v134, 0xbfb8aa3b, v118
	v_mul_f32_e32 v135, 0xbfb8aa3b, v119
	v_exp_f32_e32 v132, v132
	v_exp_f32_e32 v133, v133
	v_exp_f32_e32 v134, v134
	v_exp_f32_e32 v135, v135
	v_add_f32_e32 v132, 1.0, v132
	v_add_f32_e32 v133, 1.0, v133
	v_add_f32_e32 v134, 1.0, v134
	v_add_f32_e32 v135, 1.0, v135
	v_rcp_f32_e32 v132, v132
	v_rcp_f32_e32 v133, v133
	v_rcp_f32_e32 v134, v134
	v_rcp_f32_e32 v135, v135
	v_mul_f32_e32 v132, v116, v132
	v_mul_f32_e32 v133, v117, v133
	v_mul_f32_e32 v134, v118, v134
	v_mul_f32_e32 v135, v119, v135
	v_cvt_pk_bf16_f32 v136, v132, v133
	v_cvt_pk_bf16_f32 v137, v134, v135
	ds_write_b64 v155, v[136:137] offset:4352
	v_mul_f32_e32 v132, 0xbfb8aa3b, v112
	v_mul_f32_e32 v133, 0xbfb8aa3b, v113
	v_mul_f32_e32 v134, 0xbfb8aa3b, v114
	v_mul_f32_e32 v135, 0xbfb8aa3b, v115
	v_exp_f32_e32 v132, v132
	v_exp_f32_e32 v133, v133
	v_exp_f32_e32 v134, v134
	v_exp_f32_e32 v135, v135
	v_add_f32_e32 v132, 1.0, v132
	v_add_f32_e32 v133, 1.0, v133
	v_add_f32_e32 v134, 1.0, v134
	v_add_f32_e32 v135, 1.0, v135
	v_rcp_f32_e32 v132, v132
	v_rcp_f32_e32 v133, v133
	v_rcp_f32_e32 v134, v134
	v_rcp_f32_e32 v135, v135
	v_mul_f32_e32 v132, v112, v132
	v_mul_f32_e32 v133, v113, v133
	v_mul_f32_e32 v134, v114, v134
	v_mul_f32_e32 v135, v115, v135
	v_cvt_pk_bf16_f32 v138, v132, v133
	v_cvt_pk_bf16_f32 v139, v134, v135
	ds_write_b64 v155, v[138:139] offset:4384
	v_mul_f32_e32 v132, 0xbfb8aa3b, v108
	v_mul_f32_e32 v133, 0xbfb8aa3b, v109
	v_mul_f32_e32 v134, 0xbfb8aa3b, v110
	v_mul_f32_e32 v135, 0xbfb8aa3b, v111
	v_exp_f32_e32 v132, v132
	v_exp_f32_e32 v133, v133
	v_exp_f32_e32 v134, v134
	v_exp_f32_e32 v135, v135
	v_add_f32_e32 v132, 1.0, v132
	v_add_f32_e32 v133, 1.0, v133
	v_add_f32_e32 v134, 1.0, v134
	v_add_f32_e32 v135, 1.0, v135
	v_rcp_f32_e32 v132, v132
	v_rcp_f32_e32 v133, v133
	v_rcp_f32_e32 v134, v134
	v_rcp_f32_e32 v135, v135
	v_mul_f32_e32 v132, v108, v132
	v_mul_f32_e32 v133, v109, v133
	v_mul_f32_e32 v134, v110, v134
	v_mul_f32_e32 v135, v111, v135
	v_cvt_pk_bf16_f32 v136, v132, v133
	v_cvt_pk_bf16_f32 v137, v134, v135
	ds_write_b64 v155, v[136:137] offset:8704
	v_mul_f32_e32 v132, 0xbfb8aa3b, v104
	v_mul_f32_e32 v133, 0xbfb8aa3b, v105
	v_mul_f32_e32 v134, 0xbfb8aa3b, v106
	v_mul_f32_e32 v135, 0xbfb8aa3b, v107
	v_exp_f32_e32 v132, v132
	v_exp_f32_e32 v133, v133
	v_exp_f32_e32 v134, v134
	v_exp_f32_e32 v135, v135
	v_add_f32_e32 v132, 1.0, v132
	v_add_f32_e32 v133, 1.0, v133
	v_add_f32_e32 v134, 1.0, v134
	v_add_f32_e32 v135, 1.0, v135
	v_rcp_f32_e32 v132, v132
	v_rcp_f32_e32 v133, v133
	v_rcp_f32_e32 v134, v134
	v_rcp_f32_e32 v135, v135
	v_mul_f32_e32 v132, v104, v132
	v_mul_f32_e32 v133, v105, v133
	v_mul_f32_e32 v134, v106, v134
	v_mul_f32_e32 v135, v107, v135
	v_cvt_pk_bf16_f32 v138, v132, v133
	v_cvt_pk_bf16_f32 v139, v134, v135
	ds_write_b64 v155, v[138:139] offset:8736
	v_mul_f32_e32 v132, 0xbfb8aa3b, v100
	v_mul_f32_e32 v133, 0xbfb8aa3b, v101
	v_mul_f32_e32 v134, 0xbfb8aa3b, v102
	v_mul_f32_e32 v135, 0xbfb8aa3b, v103
	v_exp_f32_e32 v132, v132
	v_exp_f32_e32 v133, v133
	v_exp_f32_e32 v134, v134
	v_exp_f32_e32 v135, v135
	v_add_f32_e32 v132, 1.0, v132
	v_add_f32_e32 v133, 1.0, v133
	v_add_f32_e32 v134, 1.0, v134
	v_add_f32_e32 v135, 1.0, v135
	v_rcp_f32_e32 v132, v132
	v_rcp_f32_e32 v133, v133
	v_rcp_f32_e32 v134, v134
	v_rcp_f32_e32 v135, v135
	v_mul_f32_e32 v132, v100, v132
	v_mul_f32_e32 v133, v101, v133
	v_mul_f32_e32 v134, v102, v134
	v_mul_f32_e32 v135, v103, v135
	v_cvt_pk_bf16_f32 v136, v132, v133
	v_cvt_pk_bf16_f32 v137, v134, v135
	ds_write_b64 v155, v[136:137] offset:13056
	v_mul_f32_e32 v132, 0xbfb8aa3b, v96
	v_mul_f32_e32 v133, 0xbfb8aa3b, v97
	v_mul_f32_e32 v134, 0xbfb8aa3b, v98
	v_mul_f32_e32 v135, 0xbfb8aa3b, v99
	v_exp_f32_e32 v132, v132
	v_exp_f32_e32 v133, v133
	v_exp_f32_e32 v134, v134
	v_exp_f32_e32 v135, v135
	v_add_f32_e32 v132, 1.0, v132
	v_add_f32_e32 v133, 1.0, v133
	v_add_f32_e32 v134, 1.0, v134
	v_add_f32_e32 v135, 1.0, v135
	v_rcp_f32_e32 v132, v132
	v_rcp_f32_e32 v133, v133
	v_rcp_f32_e32 v134, v134
	v_rcp_f32_e32 v135, v135
	v_mul_f32_e32 v132, v96, v132
	v_mul_f32_e32 v133, v97, v133
	v_mul_f32_e32 v134, v98, v134
	v_mul_f32_e32 v135, v99, v135
	v_cvt_pk_bf16_f32 v138, v132, v133
	v_cvt_pk_bf16_f32 v139, v134, v135
	ds_write_b64 v155, v[138:139] offset:13088
	s_waitcnt lgkmcnt(0)
	s_barrier
	ds_read_b128 v[132:135], v156 offset:0
	ds_read_b128 v[136:139], v156 offset:8704
	s_add_u32 s8, s6, 0x0
	s_addc_u32 s9, s7, 0
	s_waitcnt lgkmcnt(1)
	global_store_dwordx4 v157, v[132:135], s[8:9] sc1
	s_add_u32 s8, s6, 0x10000
	s_addc_u32 s9, s7, 0
	s_waitcnt lgkmcnt(0)
	global_store_dwordx4 v157, v[136:139], s[8:9] sc1
	ds_read_b128 v[132:135], v156 offset:17408
	ds_read_b128 v[136:139], v156 offset:26112
	s_add_u32 s8, s6, 0x20000
	s_addc_u32 s9, s7, 0
	s_waitcnt lgkmcnt(1)
	global_store_dwordx4 v157, v[132:135], s[8:9] sc1
	s_add_u32 s8, s6, 0x30000
	s_addc_u32 s9, s7, 0
	s_waitcnt lgkmcnt(0)
	global_store_dwordx4 v157, v[136:139], s[8:9] sc1
	s_barrier
	v_mul_f32_e32 v132, 0xbfb8aa3b, v92
	v_mul_f32_e32 v133, 0xbfb8aa3b, v93
	v_mul_f32_e32 v134, 0xbfb8aa3b, v94
	v_mul_f32_e32 v135, 0xbfb8aa3b, v95
	v_exp_f32_e32 v132, v132
	v_exp_f32_e32 v133, v133
	v_exp_f32_e32 v134, v134
	v_exp_f32_e32 v135, v135
	v_add_f32_e32 v132, 1.0, v132
	v_add_f32_e32 v133, 1.0, v133
	v_add_f32_e32 v134, 1.0, v134
	v_add_f32_e32 v135, 1.0, v135
	v_rcp_f32_e32 v132, v132
	v_rcp_f32_e32 v133, v133
	v_rcp_f32_e32 v134, v134
	v_rcp_f32_e32 v135, v135
	v_mul_f32_e32 v132, v92, v132
	v_mul_f32_e32 v133, v93, v133
	v_mul_f32_e32 v134, v94, v134
	v_mul_f32_e32 v135, v95, v135
	v_cvt_pk_bf16_f32 v136, v132, v133
	v_cvt_pk_bf16_f32 v137, v134, v135
	ds_write_b64 v155, v[136:137] offset:0
	v_mul_f32_e32 v132, 0xbfb8aa3b, v88
	v_mul_f32_e32 v133, 0xbfb8aa3b, v89
	v_mul_f32_e32 v134, 0xbfb8aa3b, v90
	v_mul_f32_e32 v135, 0xbfb8aa3b, v91
	v_exp_f32_e32 v132, v132
	v_exp_f32_e32 v133, v133
	v_exp_f32_e32 v134, v134
	v_exp_f32_e32 v135, v135
	v_add_f32_e32 v132, 1.0, v132
	v_add_f32_e32 v133, 1.0, v133
	v_add_f32_e32 v134, 1.0, v134
	v_add_f32_e32 v135, 1.0, v135
	v_rcp_f32_e32 v132, v132
	v_rcp_f32_e32 v133, v133
	v_rcp_f32_e32 v134, v134
	v_rcp_f32_e32 v135, v135
	v_mul_f32_e32 v132, v88, v132
	v_mul_f32_e32 v133, v89, v133
	v_mul_f32_e32 v134, v90, v134
	v_mul_f32_e32 v135, v91, v135
	v_cvt_pk_bf16_f32 v138, v132, v133
	v_cvt_pk_bf16_f32 v139, v134, v135
	ds_write_b64 v155, v[138:139] offset:32
	v_mul_f32_e32 v132, 0xbfb8aa3b, v84
	v_mul_f32_e32 v133, 0xbfb8aa3b, v85
	v_mul_f32_e32 v134, 0xbfb8aa3b, v86
	v_mul_f32_e32 v135, 0xbfb8aa3b, v87
	v_exp_f32_e32 v132, v132
	v_exp_f32_e32 v133, v133
	v_exp_f32_e32 v134, v134
	v_exp_f32_e32 v135, v135
	v_add_f32_e32 v132, 1.0, v132
	v_add_f32_e32 v133, 1.0, v133
	v_add_f32_e32 v134, 1.0, v134
	v_add_f32_e32 v135, 1.0, v135
	v_rcp_f32_e32 v132, v132
	v_rcp_f32_e32 v133, v133
	v_rcp_f32_e32 v134, v134
	v_rcp_f32_e32 v135, v135
	v_mul_f32_e32 v132, v84, v132
	v_mul_f32_e32 v133, v85, v133
	v_mul_f32_e32 v134, v86, v134
	v_mul_f32_e32 v135, v87, v135
	v_cvt_pk_bf16_f32 v136, v132, v133
	v_cvt_pk_bf16_f32 v137, v134, v135
	ds_write_b64 v155, v[136:137] offset:4352
	v_mul_f32_e32 v132, 0xbfb8aa3b, v80
	v_mul_f32_e32 v133, 0xbfb8aa3b, v81
	v_mul_f32_e32 v134, 0xbfb8aa3b, v82
	v_mul_f32_e32 v135, 0xbfb8aa3b, v83
	v_exp_f32_e32 v132, v132
	v_exp_f32_e32 v133, v133
	v_exp_f32_e32 v134, v134
	v_exp_f32_e32 v135, v135
	v_add_f32_e32 v132, 1.0, v132
	v_add_f32_e32 v133, 1.0, v133
	v_add_f32_e32 v134, 1.0, v134
	v_add_f32_e32 v135, 1.0, v135
	v_rcp_f32_e32 v132, v132
	v_rcp_f32_e32 v133, v133
	v_rcp_f32_e32 v134, v134
	v_rcp_f32_e32 v135, v135
	v_mul_f32_e32 v132, v80, v132
	v_mul_f32_e32 v133, v81, v133
	v_mul_f32_e32 v134, v82, v134
	v_mul_f32_e32 v135, v83, v135
	v_cvt_pk_bf16_f32 v138, v132, v133
	v_cvt_pk_bf16_f32 v139, v134, v135
	ds_write_b64 v155, v[138:139] offset:4384
	v_mul_f32_e32 v132, 0xbfb8aa3b, v76
	v_mul_f32_e32 v133, 0xbfb8aa3b, v77
	v_mul_f32_e32 v134, 0xbfb8aa3b, v78
	v_mul_f32_e32 v135, 0xbfb8aa3b, v79
	v_exp_f32_e32 v132, v132
	v_exp_f32_e32 v133, v133
	v_exp_f32_e32 v134, v134
	v_exp_f32_e32 v135, v135
	v_add_f32_e32 v132, 1.0, v132
	v_add_f32_e32 v133, 1.0, v133
	v_add_f32_e32 v134, 1.0, v134
	v_add_f32_e32 v135, 1.0, v135
	v_rcp_f32_e32 v132, v132
	v_rcp_f32_e32 v133, v133
	v_rcp_f32_e32 v134, v134
	v_rcp_f32_e32 v135, v135
	v_mul_f32_e32 v132, v76, v132
	v_mul_f32_e32 v133, v77, v133
	v_mul_f32_e32 v134, v78, v134
	v_mul_f32_e32 v135, v79, v135
	v_cvt_pk_bf16_f32 v136, v132, v133
	v_cvt_pk_bf16_f32 v137, v134, v135
	ds_write_b64 v155, v[136:137] offset:8704
	v_mul_f32_e32 v132, 0xbfb8aa3b, v72
	v_mul_f32_e32 v133, 0xbfb8aa3b, v73
	v_mul_f32_e32 v134, 0xbfb8aa3b, v74
	v_mul_f32_e32 v135, 0xbfb8aa3b, v75
	v_exp_f32_e32 v132, v132
	v_exp_f32_e32 v133, v133
	v_exp_f32_e32 v134, v134
	v_exp_f32_e32 v135, v135
	v_add_f32_e32 v132, 1.0, v132
	v_add_f32_e32 v133, 1.0, v133
	v_add_f32_e32 v134, 1.0, v134
	v_add_f32_e32 v135, 1.0, v135
	v_rcp_f32_e32 v132, v132
	v_rcp_f32_e32 v133, v133
	v_rcp_f32_e32 v134, v134
	v_rcp_f32_e32 v135, v135
	v_mul_f32_e32 v132, v72, v132
	v_mul_f32_e32 v133, v73, v133
	v_mul_f32_e32 v134, v74, v134
	v_mul_f32_e32 v135, v75, v135
	v_cvt_pk_bf16_f32 v138, v132, v133
	v_cvt_pk_bf16_f32 v139, v134, v135
	ds_write_b64 v155, v[138:139] offset:8736
	v_mul_f32_e32 v132, 0xbfb8aa3b, v68
	v_mul_f32_e32 v133, 0xbfb8aa3b, v69
	v_mul_f32_e32 v134, 0xbfb8aa3b, v70
	v_mul_f32_e32 v135, 0xbfb8aa3b, v71
	v_exp_f32_e32 v132, v132
	v_exp_f32_e32 v133, v133
	v_exp_f32_e32 v134, v134
	v_exp_f32_e32 v135, v135
	v_add_f32_e32 v132, 1.0, v132
	v_add_f32_e32 v133, 1.0, v133
	v_add_f32_e32 v134, 1.0, v134
	v_add_f32_e32 v135, 1.0, v135
	v_rcp_f32_e32 v132, v132
	v_rcp_f32_e32 v133, v133
	v_rcp_f32_e32 v134, v134
	v_rcp_f32_e32 v135, v135
	v_mul_f32_e32 v132, v68, v132
	v_mul_f32_e32 v133, v69, v133
	v_mul_f32_e32 v134, v70, v134
	v_mul_f32_e32 v135, v71, v135
	v_cvt_pk_bf16_f32 v136, v132, v133
	v_cvt_pk_bf16_f32 v137, v134, v135
	ds_write_b64 v155, v[136:137] offset:13056
	v_mul_f32_e32 v132, 0xbfb8aa3b, v64
	v_mul_f32_e32 v133, 0xbfb8aa3b, v65
	v_mul_f32_e32 v134, 0xbfb8aa3b, v66
	v_mul_f32_e32 v135, 0xbfb8aa3b, v67
	v_exp_f32_e32 v132, v132
	v_exp_f32_e32 v133, v133
	v_exp_f32_e32 v134, v134
	v_exp_f32_e32 v135, v135
	v_add_f32_e32 v132, 1.0, v132
	v_add_f32_e32 v133, 1.0, v133
	v_add_f32_e32 v134, 1.0, v134
	v_add_f32_e32 v135, 1.0, v135
	v_rcp_f32_e32 v132, v132
	v_rcp_f32_e32 v133, v133
	v_rcp_f32_e32 v134, v134
	v_rcp_f32_e32 v135, v135
	v_mul_f32_e32 v132, v64, v132
	v_mul_f32_e32 v133, v65, v133
	v_mul_f32_e32 v134, v66, v134
	v_mul_f32_e32 v135, v67, v135
	v_cvt_pk_bf16_f32 v138, v132, v133
	v_cvt_pk_bf16_f32 v139, v134, v135
	ds_write_b64 v155, v[138:139] offset:13088
	s_waitcnt lgkmcnt(0)
	s_barrier
	ds_read_b128 v[132:135], v156 offset:0
	ds_read_b128 v[136:139], v156 offset:8704
	s_add_u32 s8, s6, 0x100
	s_addc_u32 s9, s7, 0
	s_waitcnt lgkmcnt(1)
	global_store_dwordx4 v157, v[132:135], s[8:9] sc1
	s_add_u32 s8, s6, 0x10100
	s_addc_u32 s9, s7, 0
	s_waitcnt lgkmcnt(0)
	global_store_dwordx4 v157, v[136:139], s[8:9] sc1
	ds_read_b128 v[132:135], v156 offset:17408
	ds_read_b128 v[136:139], v156 offset:26112
	s_add_u32 s8, s6, 0x20100
	s_addc_u32 s9, s7, 0
	s_waitcnt lgkmcnt(1)
	global_store_dwordx4 v157, v[132:135], s[8:9] sc1
	s_add_u32 s8, s6, 0x30100
	s_addc_u32 s9, s7, 0
	s_waitcnt lgkmcnt(0)
	global_store_dwordx4 v157, v[136:139], s[8:9] sc1
	s_barrier
	v_mul_f32_e32 v132, 0xbfb8aa3b, v60
	v_mul_f32_e32 v133, 0xbfb8aa3b, v61
	v_mul_f32_e32 v134, 0xbfb8aa3b, v62
	v_mul_f32_e32 v135, 0xbfb8aa3b, v63
	v_exp_f32_e32 v132, v132
	v_exp_f32_e32 v133, v133
	v_exp_f32_e32 v134, v134
	v_exp_f32_e32 v135, v135
	v_add_f32_e32 v132, 1.0, v132
	v_add_f32_e32 v133, 1.0, v133
	v_add_f32_e32 v134, 1.0, v134
	v_add_f32_e32 v135, 1.0, v135
	v_rcp_f32_e32 v132, v132
	v_rcp_f32_e32 v133, v133
	v_rcp_f32_e32 v134, v134
	v_rcp_f32_e32 v135, v135
	v_mul_f32_e32 v132, v60, v132
	v_mul_f32_e32 v133, v61, v133
	v_mul_f32_e32 v134, v62, v134
	v_mul_f32_e32 v135, v63, v135
	v_cvt_pk_bf16_f32 v136, v132, v133
	v_cvt_pk_bf16_f32 v137, v134, v135
	ds_write_b64 v155, v[136:137] offset:0
	v_mul_f32_e32 v132, 0xbfb8aa3b, v56
	v_mul_f32_e32 v133, 0xbfb8aa3b, v57
	v_mul_f32_e32 v134, 0xbfb8aa3b, v58
	v_mul_f32_e32 v135, 0xbfb8aa3b, v59
	v_exp_f32_e32 v132, v132
	v_exp_f32_e32 v133, v133
	v_exp_f32_e32 v134, v134
	v_exp_f32_e32 v135, v135
	v_add_f32_e32 v132, 1.0, v132
	v_add_f32_e32 v133, 1.0, v133
	v_add_f32_e32 v134, 1.0, v134
	v_add_f32_e32 v135, 1.0, v135
	v_rcp_f32_e32 v132, v132
	v_rcp_f32_e32 v133, v133
	v_rcp_f32_e32 v134, v134
	v_rcp_f32_e32 v135, v135
	v_mul_f32_e32 v132, v56, v132
	v_mul_f32_e32 v133, v57, v133
	v_mul_f32_e32 v134, v58, v134
	v_mul_f32_e32 v135, v59, v135
	v_cvt_pk_bf16_f32 v138, v132, v133
	v_cvt_pk_bf16_f32 v139, v134, v135
	ds_write_b64 v155, v[138:139] offset:32
	v_mul_f32_e32 v132, 0xbfb8aa3b, v52
	v_mul_f32_e32 v133, 0xbfb8aa3b, v53
	v_mul_f32_e32 v134, 0xbfb8aa3b, v54
	v_mul_f32_e32 v135, 0xbfb8aa3b, v55
	v_exp_f32_e32 v132, v132
	v_exp_f32_e32 v133, v133
	v_exp_f32_e32 v134, v134
	v_exp_f32_e32 v135, v135
	v_add_f32_e32 v132, 1.0, v132
	v_add_f32_e32 v133, 1.0, v133
	v_add_f32_e32 v134, 1.0, v134
	v_add_f32_e32 v135, 1.0, v135
	v_rcp_f32_e32 v132, v132
	v_rcp_f32_e32 v133, v133
	v_rcp_f32_e32 v134, v134
	v_rcp_f32_e32 v135, v135
	v_mul_f32_e32 v132, v52, v132
	v_mul_f32_e32 v133, v53, v133
	v_mul_f32_e32 v134, v54, v134
	v_mul_f32_e32 v135, v55, v135
	v_cvt_pk_bf16_f32 v136, v132, v133
	v_cvt_pk_bf16_f32 v137, v134, v135
	ds_write_b64 v155, v[136:137] offset:4352
	v_mul_f32_e32 v132, 0xbfb8aa3b, v48
	v_mul_f32_e32 v133, 0xbfb8aa3b, v49
	v_mul_f32_e32 v134, 0xbfb8aa3b, v50
	v_mul_f32_e32 v135, 0xbfb8aa3b, v51
	v_exp_f32_e32 v132, v132
	v_exp_f32_e32 v133, v133
	v_exp_f32_e32 v134, v134
	v_exp_f32_e32 v135, v135
	v_add_f32_e32 v132, 1.0, v132
	v_add_f32_e32 v133, 1.0, v133
	v_add_f32_e32 v134, 1.0, v134
	v_add_f32_e32 v135, 1.0, v135
	v_rcp_f32_e32 v132, v132
	v_rcp_f32_e32 v133, v133
	v_rcp_f32_e32 v134, v134
	v_rcp_f32_e32 v135, v135
	v_mul_f32_e32 v132, v48, v132
	v_mul_f32_e32 v133, v49, v133
	v_mul_f32_e32 v134, v50, v134
	v_mul_f32_e32 v135, v51, v135
	v_cvt_pk_bf16_f32 v138, v132, v133
	v_cvt_pk_bf16_f32 v139, v134, v135
	ds_write_b64 v155, v[138:139] offset:4384
	v_mul_f32_e32 v132, 0xbfb8aa3b, v44
	v_mul_f32_e32 v133, 0xbfb8aa3b, v45
	v_mul_f32_e32 v134, 0xbfb8aa3b, v46
	v_mul_f32_e32 v135, 0xbfb8aa3b, v47
	v_exp_f32_e32 v132, v132
	v_exp_f32_e32 v133, v133
	v_exp_f32_e32 v134, v134
	v_exp_f32_e32 v135, v135
	v_add_f32_e32 v132, 1.0, v132
	v_add_f32_e32 v133, 1.0, v133
	v_add_f32_e32 v134, 1.0, v134
	v_add_f32_e32 v135, 1.0, v135
	v_rcp_f32_e32 v132, v132
	v_rcp_f32_e32 v133, v133
	v_rcp_f32_e32 v134, v134
	v_rcp_f32_e32 v135, v135
	v_mul_f32_e32 v132, v44, v132
	v_mul_f32_e32 v133, v45, v133
	v_mul_f32_e32 v134, v46, v134
	v_mul_f32_e32 v135, v47, v135
	v_cvt_pk_bf16_f32 v136, v132, v133
	v_cvt_pk_bf16_f32 v137, v134, v135
	ds_write_b64 v155, v[136:137] offset:8704
	v_mul_f32_e32 v132, 0xbfb8aa3b, v40
	v_mul_f32_e32 v133, 0xbfb8aa3b, v41
	v_mul_f32_e32 v134, 0xbfb8aa3b, v42
	v_mul_f32_e32 v135, 0xbfb8aa3b, v43
	v_exp_f32_e32 v132, v132
	v_exp_f32_e32 v133, v133
	v_exp_f32_e32 v134, v134
	v_exp_f32_e32 v135, v135
	v_add_f32_e32 v132, 1.0, v132
	v_add_f32_e32 v133, 1.0, v133
	v_add_f32_e32 v134, 1.0, v134
	v_add_f32_e32 v135, 1.0, v135
	v_rcp_f32_e32 v132, v132
	v_rcp_f32_e32 v133, v133
	v_rcp_f32_e32 v134, v134
	v_rcp_f32_e32 v135, v135
	v_mul_f32_e32 v132, v40, v132
	v_mul_f32_e32 v133, v41, v133
	v_mul_f32_e32 v134, v42, v134
	v_mul_f32_e32 v135, v43, v135
	v_cvt_pk_bf16_f32 v138, v132, v133
	v_cvt_pk_bf16_f32 v139, v134, v135
	ds_write_b64 v155, v[138:139] offset:8736
	v_mul_f32_e32 v132, 0xbfb8aa3b, v36
	v_mul_f32_e32 v133, 0xbfb8aa3b, v37
	v_mul_f32_e32 v134, 0xbfb8aa3b, v38
	v_mul_f32_e32 v135, 0xbfb8aa3b, v39
	v_exp_f32_e32 v132, v132
	v_exp_f32_e32 v133, v133
	v_exp_f32_e32 v134, v134
	v_exp_f32_e32 v135, v135
	v_add_f32_e32 v132, 1.0, v132
	v_add_f32_e32 v133, 1.0, v133
	v_add_f32_e32 v134, 1.0, v134
	v_add_f32_e32 v135, 1.0, v135
	v_rcp_f32_e32 v132, v132
	v_rcp_f32_e32 v133, v133
	v_rcp_f32_e32 v134, v134
	v_rcp_f32_e32 v135, v135
	v_mul_f32_e32 v132, v36, v132
	v_mul_f32_e32 v133, v37, v133
	v_mul_f32_e32 v134, v38, v134
	v_mul_f32_e32 v135, v39, v135
	v_cvt_pk_bf16_f32 v136, v132, v133
	v_cvt_pk_bf16_f32 v137, v134, v135
	ds_write_b64 v155, v[136:137] offset:13056
	v_mul_f32_e32 v132, 0xbfb8aa3b, v32
	v_mul_f32_e32 v133, 0xbfb8aa3b, v33
	v_mul_f32_e32 v134, 0xbfb8aa3b, v34
	v_mul_f32_e32 v135, 0xbfb8aa3b, v35
	v_exp_f32_e32 v132, v132
	v_exp_f32_e32 v133, v133
	v_exp_f32_e32 v134, v134
	v_exp_f32_e32 v135, v135
	v_add_f32_e32 v132, 1.0, v132
	v_add_f32_e32 v133, 1.0, v133
	v_add_f32_e32 v134, 1.0, v134
	v_add_f32_e32 v135, 1.0, v135
	v_rcp_f32_e32 v132, v132
	v_rcp_f32_e32 v133, v133
	v_rcp_f32_e32 v134, v134
	v_rcp_f32_e32 v135, v135
	v_mul_f32_e32 v132, v32, v132
	v_mul_f32_e32 v133, v33, v133
	v_mul_f32_e32 v134, v34, v134
	v_mul_f32_e32 v135, v35, v135
	v_cvt_pk_bf16_f32 v138, v132, v133
	v_cvt_pk_bf16_f32 v139, v134, v135
	ds_write_b64 v155, v[138:139] offset:13088
	s_waitcnt lgkmcnt(0)
	s_barrier
	ds_read_b128 v[132:135], v156 offset:0
	ds_read_b128 v[136:139], v156 offset:8704
	s_add_u32 s8, s6, 0x40000
	s_addc_u32 s9, s7, 0
	s_waitcnt lgkmcnt(1)
	global_store_dwordx4 v157, v[132:135], s[8:9] sc1
	s_add_u32 s8, s6, 0x50000
	s_addc_u32 s9, s7, 0
	s_waitcnt lgkmcnt(0)
	global_store_dwordx4 v157, v[136:139], s[8:9] sc1
	ds_read_b128 v[132:135], v156 offset:17408
	ds_read_b128 v[136:139], v156 offset:26112
	s_add_u32 s8, s6, 0x60000
	s_addc_u32 s9, s7, 0
	s_waitcnt lgkmcnt(1)
	global_store_dwordx4 v157, v[132:135], s[8:9] sc1
	s_add_u32 s8, s6, 0x70000
	s_addc_u32 s9, s7, 0
	s_waitcnt lgkmcnt(0)
	global_store_dwordx4 v157, v[136:139], s[8:9] sc1
	s_barrier
	v_mul_f32_e32 v132, 0xbfb8aa3b, v28
	v_mul_f32_e32 v133, 0xbfb8aa3b, v29
	v_mul_f32_e32 v134, 0xbfb8aa3b, v30
	v_mul_f32_e32 v135, 0xbfb8aa3b, v31
	v_exp_f32_e32 v132, v132
	v_exp_f32_e32 v133, v133
	v_exp_f32_e32 v134, v134
	v_exp_f32_e32 v135, v135
	v_add_f32_e32 v132, 1.0, v132
	v_add_f32_e32 v133, 1.0, v133
	v_add_f32_e32 v134, 1.0, v134
	v_add_f32_e32 v135, 1.0, v135
	v_rcp_f32_e32 v132, v132
	v_rcp_f32_e32 v133, v133
	v_rcp_f32_e32 v134, v134
	v_rcp_f32_e32 v135, v135
	v_mul_f32_e32 v132, v28, v132
	v_mul_f32_e32 v133, v29, v133
	v_mul_f32_e32 v134, v30, v134
	v_mul_f32_e32 v135, v31, v135
	v_cvt_pk_bf16_f32 v136, v132, v133
	v_cvt_pk_bf16_f32 v137, v134, v135
	ds_write_b64 v155, v[136:137] offset:0
	v_mul_f32_e32 v132, 0xbfb8aa3b, v24
	v_mul_f32_e32 v133, 0xbfb8aa3b, v25
	v_mul_f32_e32 v134, 0xbfb8aa3b, v26
	v_mul_f32_e32 v135, 0xbfb8aa3b, v27
	v_exp_f32_e32 v132, v132
	v_exp_f32_e32 v133, v133
	v_exp_f32_e32 v134, v134
	v_exp_f32_e32 v135, v135
	v_add_f32_e32 v132, 1.0, v132
	v_add_f32_e32 v133, 1.0, v133
	v_add_f32_e32 v134, 1.0, v134
	v_add_f32_e32 v135, 1.0, v135
	v_rcp_f32_e32 v132, v132
	v_rcp_f32_e32 v133, v133
	v_rcp_f32_e32 v134, v134
	v_rcp_f32_e32 v135, v135
	v_mul_f32_e32 v132, v24, v132
	v_mul_f32_e32 v133, v25, v133
	v_mul_f32_e32 v134, v26, v134
	v_mul_f32_e32 v135, v27, v135
	v_cvt_pk_bf16_f32 v138, v132, v133
	v_cvt_pk_bf16_f32 v139, v134, v135
	ds_write_b64 v155, v[138:139] offset:32
	v_mul_f32_e32 v132, 0xbfb8aa3b, v20
	v_mul_f32_e32 v133, 0xbfb8aa3b, v21
	v_mul_f32_e32 v134, 0xbfb8aa3b, v22
	v_mul_f32_e32 v135, 0xbfb8aa3b, v23
	v_exp_f32_e32 v132, v132
	v_exp_f32_e32 v133, v133
	v_exp_f32_e32 v134, v134
	v_exp_f32_e32 v135, v135
	v_add_f32_e32 v132, 1.0, v132
	v_add_f32_e32 v133, 1.0, v133
	v_add_f32_e32 v134, 1.0, v134
	v_add_f32_e32 v135, 1.0, v135
	v_rcp_f32_e32 v132, v132
	v_rcp_f32_e32 v133, v133
	v_rcp_f32_e32 v134, v134
	v_rcp_f32_e32 v135, v135
	v_mul_f32_e32 v132, v20, v132
	v_mul_f32_e32 v133, v21, v133
	v_mul_f32_e32 v134, v22, v134
	v_mul_f32_e32 v135, v23, v135
	v_cvt_pk_bf16_f32 v136, v132, v133
	v_cvt_pk_bf16_f32 v137, v134, v135
	ds_write_b64 v155, v[136:137] offset:4352
	v_mul_f32_e32 v132, 0xbfb8aa3b, v16
	v_mul_f32_e32 v133, 0xbfb8aa3b, v17
	v_mul_f32_e32 v134, 0xbfb8aa3b, v18
	v_mul_f32_e32 v135, 0xbfb8aa3b, v19
	v_exp_f32_e32 v132, v132
	v_exp_f32_e32 v133, v133
	v_exp_f32_e32 v134, v134
	v_exp_f32_e32 v135, v135
	v_add_f32_e32 v132, 1.0, v132
	v_add_f32_e32 v133, 1.0, v133
	v_add_f32_e32 v134, 1.0, v134
	v_add_f32_e32 v135, 1.0, v135
	v_rcp_f32_e32 v132, v132
	v_rcp_f32_e32 v133, v133
	v_rcp_f32_e32 v134, v134
	v_rcp_f32_e32 v135, v135
	v_mul_f32_e32 v132, v16, v132
	v_mul_f32_e32 v133, v17, v133
	v_mul_f32_e32 v134, v18, v134
	v_mul_f32_e32 v135, v19, v135
	v_cvt_pk_bf16_f32 v138, v132, v133
	v_cvt_pk_bf16_f32 v139, v134, v135
	ds_write_b64 v155, v[138:139] offset:4384
	v_mul_f32_e32 v132, 0xbfb8aa3b, v12
	v_mul_f32_e32 v133, 0xbfb8aa3b, v13
	v_mul_f32_e32 v134, 0xbfb8aa3b, v14
	v_mul_f32_e32 v135, 0xbfb8aa3b, v15
	v_exp_f32_e32 v132, v132
	v_exp_f32_e32 v133, v133
	v_exp_f32_e32 v134, v134
	v_exp_f32_e32 v135, v135
	v_add_f32_e32 v132, 1.0, v132
	v_add_f32_e32 v133, 1.0, v133
	v_add_f32_e32 v134, 1.0, v134
	v_add_f32_e32 v135, 1.0, v135
	v_rcp_f32_e32 v132, v132
	v_rcp_f32_e32 v133, v133
	v_rcp_f32_e32 v134, v134
	v_rcp_f32_e32 v135, v135
	v_mul_f32_e32 v132, v12, v132
	v_mul_f32_e32 v133, v13, v133
	v_mul_f32_e32 v134, v14, v134
	v_mul_f32_e32 v135, v15, v135
	v_cvt_pk_bf16_f32 v136, v132, v133
	v_cvt_pk_bf16_f32 v137, v134, v135
	ds_write_b64 v155, v[136:137] offset:8704
	v_mul_f32_e32 v132, 0xbfb8aa3b, v8
	v_mul_f32_e32 v133, 0xbfb8aa3b, v9
	v_mul_f32_e32 v134, 0xbfb8aa3b, v10
	v_mul_f32_e32 v135, 0xbfb8aa3b, v11
	v_exp_f32_e32 v132, v132
	v_exp_f32_e32 v133, v133
	v_exp_f32_e32 v134, v134
	v_exp_f32_e32 v135, v135
	v_add_f32_e32 v132, 1.0, v132
	v_add_f32_e32 v133, 1.0, v133
	v_add_f32_e32 v134, 1.0, v134
	v_add_f32_e32 v135, 1.0, v135
	v_rcp_f32_e32 v132, v132
	v_rcp_f32_e32 v133, v133
	v_rcp_f32_e32 v134, v134
	v_rcp_f32_e32 v135, v135
	v_mul_f32_e32 v132, v8, v132
	v_mul_f32_e32 v133, v9, v133
	v_mul_f32_e32 v134, v10, v134
	v_mul_f32_e32 v135, v11, v135
	v_cvt_pk_bf16_f32 v138, v132, v133
	v_cvt_pk_bf16_f32 v139, v134, v135
	ds_write_b64 v155, v[138:139] offset:8736
	v_mul_f32_e32 v132, 0xbfb8aa3b, v4
	v_mul_f32_e32 v133, 0xbfb8aa3b, v5
	v_mul_f32_e32 v134, 0xbfb8aa3b, v6
	v_mul_f32_e32 v135, 0xbfb8aa3b, v7
	v_exp_f32_e32 v132, v132
	v_exp_f32_e32 v133, v133
	v_exp_f32_e32 v134, v134
	v_exp_f32_e32 v135, v135
	v_add_f32_e32 v132, 1.0, v132
	v_add_f32_e32 v133, 1.0, v133
	v_add_f32_e32 v134, 1.0, v134
	v_add_f32_e32 v135, 1.0, v135
	v_rcp_f32_e32 v132, v132
	v_rcp_f32_e32 v133, v133
	v_rcp_f32_e32 v134, v134
	v_rcp_f32_e32 v135, v135
	v_mul_f32_e32 v132, v4, v132
	v_mul_f32_e32 v133, v5, v133
	v_mul_f32_e32 v134, v6, v134
	v_mul_f32_e32 v135, v7, v135
	v_cvt_pk_bf16_f32 v136, v132, v133
	v_cvt_pk_bf16_f32 v137, v134, v135
	ds_write_b64 v155, v[136:137] offset:13056
	v_mul_f32_e32 v132, 0xbfb8aa3b, v0
	v_mul_f32_e32 v133, 0xbfb8aa3b, v1
	v_mul_f32_e32 v134, 0xbfb8aa3b, v2
	v_mul_f32_e32 v135, 0xbfb8aa3b, v3
	v_exp_f32_e32 v132, v132
	v_exp_f32_e32 v133, v133
	v_exp_f32_e32 v134, v134
	v_exp_f32_e32 v135, v135
	v_add_f32_e32 v132, 1.0, v132
	v_add_f32_e32 v133, 1.0, v133
	v_add_f32_e32 v134, 1.0, v134
	v_add_f32_e32 v135, 1.0, v135
	v_rcp_f32_e32 v132, v132
	v_rcp_f32_e32 v133, v133
	v_rcp_f32_e32 v134, v134
	v_rcp_f32_e32 v135, v135
	v_mul_f32_e32 v132, v0, v132
	v_mul_f32_e32 v133, v1, v133
	v_mul_f32_e32 v134, v2, v134
	v_mul_f32_e32 v135, v3, v135
	v_cvt_pk_bf16_f32 v138, v132, v133
	v_cvt_pk_bf16_f32 v139, v134, v135
	ds_write_b64 v155, v[138:139] offset:13088
	s_waitcnt lgkmcnt(0)
	s_barrier
	ds_read_b128 v[132:135], v156 offset:0
	ds_read_b128 v[136:139], v156 offset:8704
	s_add_u32 s8, s6, 0x40100
	s_addc_u32 s9, s7, 0
	s_waitcnt lgkmcnt(1)
	global_store_dwordx4 v157, v[132:135], s[8:9] sc1
	s_add_u32 s8, s6, 0x50100
	s_addc_u32 s9, s7, 0
	s_waitcnt lgkmcnt(0)
	global_store_dwordx4 v157, v[136:139], s[8:9] sc1
	ds_read_b128 v[132:135], v156 offset:17408
	ds_read_b128 v[136:139], v156 offset:26112
	s_add_u32 s8, s6, 0x60100
	s_addc_u32 s9, s7, 0
	s_waitcnt lgkmcnt(1)
	global_store_dwordx4 v157, v[132:135], s[8:9] sc1
	s_add_u32 s8, s6, 0x70100
	s_addc_u32 s9, s7, 0
	s_waitcnt lgkmcnt(0)
	global_store_dwordx4 v157, v[136:139], s[8:9] sc1
	s_barrier
	s_branch .LBB0_93
.Lipe_mg:
	s_lshl_b32 s8, s4, 12
	s_sub_u32 s11, s96, 0x1800
	s_lshl_b32 s11, s11, 1
	s_add_u32 s8, s8, s11
	s_add_u32 s6, s52, s8
	s_addc_u32 s7, s53, 0
	v_and_b32_e32 v158, 63, v148
	v_lshrrev_b32_e32 v159, 6, v148
	v_lshrrev_b32_e32 v160, 2, v159
	v_and_b32_e32 v159, 3, v159
	v_and_b32_e32 v161, 15, v158
	v_lshrrev_b32_e32 v158, 4, v158
	v_lshl_add_u32 v160, v160, 6, v161
	v_mul_u32_u24_e32 v155, 0x110, v160
	v_lshlrev_b32_e32 v159, 6, v159
	v_lshl_add_u32 v159, v158, 3, v159
	v_add_u32_e32 v155, v155, v159
	v_lshrrev_b32_e32 v158, 4, v148
	v_and_b32_e32 v159, 15, v148
	v_mul_u32_u24_e32 v156, 0x110, v158
	v_lshl_add_u32 v156, v159, 4, v156
	v_lshlrev_b32_e32 v157, 12, v158
	v_lshl_add_u32 v157, v159, 4, v157
	v_mul_f32_e32 v132, 0xbfb8aa3b, v124
	v_mul_f32_e32 v133, 0xbfb8aa3b, v125
	v_mul_f32_e32 v134, 0xbfb8aa3b, v126
	v_mul_f32_e32 v135, 0xbfb8aa3b, v127
	v_exp_f32_e32 v132, v132
	v_exp_f32_e32 v133, v133
	v_exp_f32_e32 v134, v134
	v_exp_f32_e32 v135, v135
	v_add_f32_e32 v132, 1.0, v132
	v_add_f32_e32 v133, 1.0, v133
	v_add_f32_e32 v134, 1.0, v134
	v_add_f32_e32 v135, 1.0, v135
	v_rcp_f32_e32 v132, v132
	v_rcp_f32_e32 v133, v133
	v_rcp_f32_e32 v134, v134
	v_rcp_f32_e32 v135, v135
	s_nop 0
	v_cvt_pk_bf16_f32 v136, v132, v133
	v_cvt_pk_bf16_f32 v137, v134, v135
	ds_write_b64 v155, v[136:137] offset:0
	v_mul_f32_e32 v132, 0xbfb8aa3b, v120
	v_mul_f32_e32 v133, 0xbfb8aa3b, v121
	v_mul_f32_e32 v134, 0xbfb8aa3b, v122
	v_mul_f32_e32 v135, 0xbfb8aa3b, v123
	v_exp_f32_e32 v132, v132
	v_exp_f32_e32 v133, v133
	v_exp_f32_e32 v134, v134
	v_exp_f32_e32 v135, v135
	v_add_f32_e32 v132, 1.0, v132
	v_add_f32_e32 v133, 1.0, v133
	v_add_f32_e32 v134, 1.0, v134
	v_add_f32_e32 v135, 1.0, v135
	v_rcp_f32_e32 v132, v132
	v_rcp_f32_e32 v133, v133
	v_rcp_f32_e32 v134, v134
	v_rcp_f32_e32 v135, v135
	s_nop 0
	v_cvt_pk_bf16_f32 v138, v132, v133
	v_cvt_pk_bf16_f32 v139, v134, v135
	ds_write_b64 v155, v[138:139] offset:32
	v_mul_f32_e32 v132, 0xbfb8aa3b, v116
	v_mul_f32_e32 v133, 0xbfb8aa3b, v117
	v_mul_f32_e32 v134, 0xbfb8aa3b, v118
	v_mul_f32_e32 v135, 0xbfb8aa3b, v119
	v_exp_f32_e32 v132, v132
	v_exp_f32_e32 v133, v133
	v_exp_f32_e32 v134, v134
	v_exp_f32_e32 v135, v135
	v_add_f32_e32 v132, 1.0, v132
	v_add_f32_e32 v133, 1.0, v133
	v_add_f32_e32 v134, 1.0, v134
	v_add_f32_e32 v135, 1.0, v135
	v_rcp_f32_e32 v132, v132
	v_rcp_f32_e32 v133, v133
	v_rcp_f32_e32 v134, v134
	v_rcp_f32_e32 v135, v135
	s_nop 0
	v_cvt_pk_bf16_f32 v136, v132, v133
	v_cvt_pk_bf16_f32 v137, v134, v135
	ds_write_b64 v155, v[136:137] offset:4352
	v_mul_f32_e32 v132, 0xbfb8aa3b, v112
	v_mul_f32_e32 v133, 0xbfb8aa3b, v113
	v_mul_f32_e32 v134, 0xbfb8aa3b, v114
	v_mul_f32_e32 v135, 0xbfb8aa3b, v115
	v_exp_f32_e32 v132, v132
	v_exp_f32_e32 v133, v133
	v_exp_f32_e32 v134, v134
	v_exp_f32_e32 v135, v135
	v_add_f32_e32 v132, 1.0, v132
	v_add_f32_e32 v133, 1.0, v133
	v_add_f32_e32 v134, 1.0, v134
	v_add_f32_e32 v135, 1.0, v135
	v_rcp_f32_e32 v132, v132
	v_rcp_f32_e32 v133, v133
	v_rcp_f32_e32 v134, v134
	v_rcp_f32_e32 v135, v135
	s_nop 0
	v_cvt_pk_bf16_f32 v138, v132, v133
	v_cvt_pk_bf16_f32 v139, v134, v135
	ds_write_b64 v155, v[138:139] offset:4384
	v_mul_f32_e32 v132, 0xbfb8aa3b, v108
	v_mul_f32_e32 v133, 0xbfb8aa3b, v109
	v_mul_f32_e32 v134, 0xbfb8aa3b, v110
	v_mul_f32_e32 v135, 0xbfb8aa3b, v111
	v_exp_f32_e32 v132, v132
	v_exp_f32_e32 v133, v133
	v_exp_f32_e32 v134, v134
	v_exp_f32_e32 v135, v135
	v_add_f32_e32 v132, 1.0, v132
	v_add_f32_e32 v133, 1.0, v133
	v_add_f32_e32 v134, 1.0, v134
	v_add_f32_e32 v135, 1.0, v135
	v_rcp_f32_e32 v132, v132
	v_rcp_f32_e32 v133, v133
	v_rcp_f32_e32 v134, v134
	v_rcp_f32_e32 v135, v135
	s_nop 0
	v_cvt_pk_bf16_f32 v136, v132, v133
	v_cvt_pk_bf16_f32 v137, v134, v135
	ds_write_b64 v155, v[136:137] offset:8704
	v_mul_f32_e32 v132, 0xbfb8aa3b, v104
	v_mul_f32_e32 v133, 0xbfb8aa3b, v105
	v_mul_f32_e32 v134, 0xbfb8aa3b, v106
	v_mul_f32_e32 v135, 0xbfb8aa3b, v107
	v_exp_f32_e32 v132, v132
	v_exp_f32_e32 v133, v133
	v_exp_f32_e32 v134, v134
	v_exp_f32_e32 v135, v135
	v_add_f32_e32 v132, 1.0, v132
	v_add_f32_e32 v133, 1.0, v133
	v_add_f32_e32 v134, 1.0, v134
	v_add_f32_e32 v135, 1.0, v135
	v_rcp_f32_e32 v132, v132
	v_rcp_f32_e32 v133, v133
	v_rcp_f32_e32 v134, v134
	v_rcp_f32_e32 v135, v135
	s_nop 0
	v_cvt_pk_bf16_f32 v138, v132, v133
	v_cvt_pk_bf16_f32 v139, v134, v135
	ds_write_b64 v155, v[138:139] offset:8736
	v_mul_f32_e32 v132, 0xbfb8aa3b, v100
	v_mul_f32_e32 v133, 0xbfb8aa3b, v101
	v_mul_f32_e32 v134, 0xbfb8aa3b, v102
	v_mul_f32_e32 v135, 0xbfb8aa3b, v103
	v_exp_f32_e32 v132, v132
	v_exp_f32_e32 v133, v133
	v_exp_f32_e32 v134, v134
	v_exp_f32_e32 v135, v135
	v_add_f32_e32 v132, 1.0, v132
	v_add_f32_e32 v133, 1.0, v133
	v_add_f32_e32 v134, 1.0, v134
	v_add_f32_e32 v135, 1.0, v135
	v_rcp_f32_e32 v132, v132
	v_rcp_f32_e32 v133, v133
	v_rcp_f32_e32 v134, v134
	v_rcp_f32_e32 v135, v135
	s_nop 0
	v_cvt_pk_bf16_f32 v136, v132, v133
	v_cvt_pk_bf16_f32 v137, v134, v135
	ds_write_b64 v155, v[136:137] offset:13056
	v_mul_f32_e32 v132, 0xbfb8aa3b, v96
	v_mul_f32_e32 v133, 0xbfb8aa3b, v97
	v_mul_f32_e32 v134, 0xbfb8aa3b, v98
	v_mul_f32_e32 v135, 0xbfb8aa3b, v99
	v_exp_f32_e32 v132, v132
	v_exp_f32_e32 v133, v133
	v_exp_f32_e32 v134, v134
	v_exp_f32_e32 v135, v135
	v_add_f32_e32 v132, 1.0, v132
	v_add_f32_e32 v133, 1.0, v133
	v_add_f32_e32 v134, 1.0, v134
	v_add_f32_e32 v135, 1.0, v135
	v_rcp_f32_e32 v132, v132
	v_rcp_f32_e32 v133, v133
	v_rcp_f32_e32 v134, v134
	v_rcp_f32_e32 v135, v135
	s_nop 0
	v_cvt_pk_bf16_f32 v138, v132, v133
	v_cvt_pk_bf16_f32 v139, v134, v135
	ds_write_b64 v155, v[138:139] offset:13088
	s_waitcnt lgkmcnt(0)
	s_barrier
	ds_read_b128 v[132:135], v156 offset:0
	ds_read_b128 v[136:139], v156 offset:8704
	s_add_u32 s8, s6, 0x0
	s_addc_u32 s9, s7, 0
	s_waitcnt lgkmcnt(1)
	global_store_dwordx4 v157, v[132:135], s[8:9] sc1
	s_add_u32 s8, s6, 0x20000
	s_addc_u32 s9, s7, 0
	s_waitcnt lgkmcnt(0)
	global_store_dwordx4 v157, v[136:139], s[8:9] sc1
	ds_read_b128 v[132:135], v156 offset:17408
	ds_read_b128 v[136:139], v156 offset:26112
	s_add_u32 s8, s6, 0x40000
	s_addc_u32 s9, s7, 0
	s_waitcnt lgkmcnt(1)
	global_store_dwordx4 v157, v[132:135], s[8:9] sc1
	s_add_u32 s8, s6, 0x60000
	s_addc_u32 s9, s7, 0
	s_waitcnt lgkmcnt(0)
	global_store_dwordx4 v157, v[136:139], s[8:9] sc1
	s_barrier
	v_mul_f32_e32 v132, 0xbfb8aa3b, v92
	v_mul_f32_e32 v133, 0xbfb8aa3b, v93
	v_mul_f32_e32 v134, 0xbfb8aa3b, v94
	v_mul_f32_e32 v135, 0xbfb8aa3b, v95
	v_exp_f32_e32 v132, v132
	v_exp_f32_e32 v133, v133
	v_exp_f32_e32 v134, v134
	v_exp_f32_e32 v135, v135
	v_add_f32_e32 v132, 1.0, v132
	v_add_f32_e32 v133, 1.0, v133
	v_add_f32_e32 v134, 1.0, v134
	v_add_f32_e32 v135, 1.0, v135
	v_rcp_f32_e32 v132, v132
	v_rcp_f32_e32 v133, v133
	v_rcp_f32_e32 v134, v134
	v_rcp_f32_e32 v135, v135
	s_nop 0
	v_cvt_pk_bf16_f32 v136, v132, v133
	v_cvt_pk_bf16_f32 v137, v134, v135
	ds_write_b64 v155, v[136:137] offset:0
	v_mul_f32_e32 v132, 0xbfb8aa3b, v88
	v_mul_f32_e32 v133, 0xbfb8aa3b, v89
	v_mul_f32_e32 v134, 0xbfb8aa3b, v90
	v_mul_f32_e32 v135, 0xbfb8aa3b, v91
	v_exp_f32_e32 v132, v132
	v_exp_f32_e32 v133, v133
	v_exp_f32_e32 v134, v134
	v_exp_f32_e32 v135, v135
	v_add_f32_e32 v132, 1.0, v132
	v_add_f32_e32 v133, 1.0, v133
	v_add_f32_e32 v134, 1.0, v134
	v_add_f32_e32 v135, 1.0, v135
	v_rcp_f32_e32 v132, v132
	v_rcp_f32_e32 v133, v133
	v_rcp_f32_e32 v134, v134
	v_rcp_f32_e32 v135, v135
	s_nop 0
	v_cvt_pk_bf16_f32 v138, v132, v133
	v_cvt_pk_bf16_f32 v139, v134, v135
	ds_write_b64 v155, v[138:139] offset:32
	v_mul_f32_e32 v132, 0xbfb8aa3b, v84
	v_mul_f32_e32 v133, 0xbfb8aa3b, v85
	v_mul_f32_e32 v134, 0xbfb8aa3b, v86
	v_mul_f32_e32 v135, 0xbfb8aa3b, v87
	v_exp_f32_e32 v132, v132
	v_exp_f32_e32 v133, v133
	v_exp_f32_e32 v134, v134
	v_exp_f32_e32 v135, v135
	v_add_f32_e32 v132, 1.0, v132
	v_add_f32_e32 v133, 1.0, v133
	v_add_f32_e32 v134, 1.0, v134
	v_add_f32_e32 v135, 1.0, v135
	v_rcp_f32_e32 v132, v132
	v_rcp_f32_e32 v133, v133
	v_rcp_f32_e32 v134, v134
	v_rcp_f32_e32 v135, v135
	s_nop 0
	v_cvt_pk_bf16_f32 v136, v132, v133
	v_cvt_pk_bf16_f32 v137, v134, v135
	ds_write_b64 v155, v[136:137] offset:4352
	v_mul_f32_e32 v132, 0xbfb8aa3b, v80
	v_mul_f32_e32 v133, 0xbfb8aa3b, v81
	v_mul_f32_e32 v134, 0xbfb8aa3b, v82
	v_mul_f32_e32 v135, 0xbfb8aa3b, v83
	v_exp_f32_e32 v132, v132
	v_exp_f32_e32 v133, v133
	v_exp_f32_e32 v134, v134
	v_exp_f32_e32 v135, v135
	v_add_f32_e32 v132, 1.0, v132
	v_add_f32_e32 v133, 1.0, v133
	v_add_f32_e32 v134, 1.0, v134
	v_add_f32_e32 v135, 1.0, v135
	v_rcp_f32_e32 v132, v132
	v_rcp_f32_e32 v133, v133
	v_rcp_f32_e32 v134, v134
	v_rcp_f32_e32 v135, v135
	s_nop 0
	v_cvt_pk_bf16_f32 v138, v132, v133
	v_cvt_pk_bf16_f32 v139, v134, v135
	ds_write_b64 v155, v[138:139] offset:4384
	v_mul_f32_e32 v132, 0xbfb8aa3b, v76
	v_mul_f32_e32 v133, 0xbfb8aa3b, v77
	v_mul_f32_e32 v134, 0xbfb8aa3b, v78
	v_mul_f32_e32 v135, 0xbfb8aa3b, v79
	v_exp_f32_e32 v132, v132
	v_exp_f32_e32 v133, v133
	v_exp_f32_e32 v134, v134
	v_exp_f32_e32 v135, v135
	v_add_f32_e32 v132, 1.0, v132
	v_add_f32_e32 v133, 1.0, v133
	v_add_f32_e32 v134, 1.0, v134
	v_add_f32_e32 v135, 1.0, v135
	v_rcp_f32_e32 v132, v132
	v_rcp_f32_e32 v133, v133
	v_rcp_f32_e32 v134, v134
	v_rcp_f32_e32 v135, v135
	s_nop 0
	v_cvt_pk_bf16_f32 v136, v132, v133
	v_cvt_pk_bf16_f32 v137, v134, v135
	ds_write_b64 v155, v[136:137] offset:8704
	v_mul_f32_e32 v132, 0xbfb8aa3b, v72
	v_mul_f32_e32 v133, 0xbfb8aa3b, v73
	v_mul_f32_e32 v134, 0xbfb8aa3b, v74
	v_mul_f32_e32 v135, 0xbfb8aa3b, v75
	v_exp_f32_e32 v132, v132
	v_exp_f32_e32 v133, v133
	v_exp_f32_e32 v134, v134
	v_exp_f32_e32 v135, v135
	v_add_f32_e32 v132, 1.0, v132
	v_add_f32_e32 v133, 1.0, v133
	v_add_f32_e32 v134, 1.0, v134
	v_add_f32_e32 v135, 1.0, v135
	v_rcp_f32_e32 v132, v132
	v_rcp_f32_e32 v133, v133
	v_rcp_f32_e32 v134, v134
	v_rcp_f32_e32 v135, v135
	s_nop 0
	v_cvt_pk_bf16_f32 v138, v132, v133
	v_cvt_pk_bf16_f32 v139, v134, v135
	ds_write_b64 v155, v[138:139] offset:8736
	v_mul_f32_e32 v132, 0xbfb8aa3b, v68
	v_mul_f32_e32 v133, 0xbfb8aa3b, v69
	v_mul_f32_e32 v134, 0xbfb8aa3b, v70
	v_mul_f32_e32 v135, 0xbfb8aa3b, v71
	v_exp_f32_e32 v132, v132
	v_exp_f32_e32 v133, v133
	v_exp_f32_e32 v134, v134
	v_exp_f32_e32 v135, v135
	v_add_f32_e32 v132, 1.0, v132
	v_add_f32_e32 v133, 1.0, v133
	v_add_f32_e32 v134, 1.0, v134
	v_add_f32_e32 v135, 1.0, v135
	v_rcp_f32_e32 v132, v132
	v_rcp_f32_e32 v133, v133
	v_rcp_f32_e32 v134, v134
	v_rcp_f32_e32 v135, v135
	s_nop 0
	v_cvt_pk_bf16_f32 v136, v132, v133
	v_cvt_pk_bf16_f32 v137, v134, v135
	ds_write_b64 v155, v[136:137] offset:13056
	v_mul_f32_e32 v132, 0xbfb8aa3b, v64
	v_mul_f32_e32 v133, 0xbfb8aa3b, v65
	v_mul_f32_e32 v134, 0xbfb8aa3b, v66
	v_mul_f32_e32 v135, 0xbfb8aa3b, v67
	v_exp_f32_e32 v132, v132
	v_exp_f32_e32 v133, v133
	v_exp_f32_e32 v134, v134
	v_exp_f32_e32 v135, v135
	v_add_f32_e32 v132, 1.0, v132
	v_add_f32_e32 v133, 1.0, v133
	v_add_f32_e32 v134, 1.0, v134
	v_add_f32_e32 v135, 1.0, v135
	v_rcp_f32_e32 v132, v132
	v_rcp_f32_e32 v133, v133
	v_rcp_f32_e32 v134, v134
	v_rcp_f32_e32 v135, v135
	s_nop 0
	v_cvt_pk_bf16_f32 v138, v132, v133
	v_cvt_pk_bf16_f32 v139, v134, v135
	ds_write_b64 v155, v[138:139] offset:13088
	s_waitcnt lgkmcnt(0)
	s_barrier
	ds_read_b128 v[132:135], v156 offset:0
	ds_read_b128 v[136:139], v156 offset:8704
	s_add_u32 s8, s6, 0x100
	s_addc_u32 s9, s7, 0
	s_waitcnt lgkmcnt(1)
	global_store_dwordx4 v157, v[132:135], s[8:9] sc1
	s_add_u32 s8, s6, 0x20100
	s_addc_u32 s9, s7, 0
	s_waitcnt lgkmcnt(0)
	global_store_dwordx4 v157, v[136:139], s[8:9] sc1
	ds_read_b128 v[132:135], v156 offset:17408
	ds_read_b128 v[136:139], v156 offset:26112
	s_add_u32 s8, s6, 0x40100
	s_addc_u32 s9, s7, 0
	s_waitcnt lgkmcnt(1)
	global_store_dwordx4 v157, v[132:135], s[8:9] sc1
	s_add_u32 s8, s6, 0x60100
	s_addc_u32 s9, s7, 0
	s_waitcnt lgkmcnt(0)
	global_store_dwordx4 v157, v[136:139], s[8:9] sc1
	s_barrier
	v_mul_f32_e32 v132, 0xbfb8aa3b, v60
	v_mul_f32_e32 v133, 0xbfb8aa3b, v61
	v_mul_f32_e32 v134, 0xbfb8aa3b, v62
	v_mul_f32_e32 v135, 0xbfb8aa3b, v63
	v_exp_f32_e32 v132, v132
	v_exp_f32_e32 v133, v133
	v_exp_f32_e32 v134, v134
	v_exp_f32_e32 v135, v135
	v_add_f32_e32 v132, 1.0, v132
	v_add_f32_e32 v133, 1.0, v133
	v_add_f32_e32 v134, 1.0, v134
	v_add_f32_e32 v135, 1.0, v135
	v_rcp_f32_e32 v132, v132
	v_rcp_f32_e32 v133, v133
	v_rcp_f32_e32 v134, v134
	v_rcp_f32_e32 v135, v135
	s_nop 0
	v_cvt_pk_bf16_f32 v136, v132, v133
	v_cvt_pk_bf16_f32 v137, v134, v135
	ds_write_b64 v155, v[136:137] offset:0
	v_mul_f32_e32 v132, 0xbfb8aa3b, v56
	v_mul_f32_e32 v133, 0xbfb8aa3b, v57
	v_mul_f32_e32 v134, 0xbfb8aa3b, v58
	v_mul_f32_e32 v135, 0xbfb8aa3b, v59
	v_exp_f32_e32 v132, v132
	v_exp_f32_e32 v133, v133
	v_exp_f32_e32 v134, v134
	v_exp_f32_e32 v135, v135
	v_add_f32_e32 v132, 1.0, v132
	v_add_f32_e32 v133, 1.0, v133
	v_add_f32_e32 v134, 1.0, v134
	v_add_f32_e32 v135, 1.0, v135
	v_rcp_f32_e32 v132, v132
	v_rcp_f32_e32 v133, v133
	v_rcp_f32_e32 v134, v134
	v_rcp_f32_e32 v135, v135
	s_nop 0
	v_cvt_pk_bf16_f32 v138, v132, v133
	v_cvt_pk_bf16_f32 v139, v134, v135
	ds_write_b64 v155, v[138:139] offset:32
	v_mul_f32_e32 v132, 0xbfb8aa3b, v52
	v_mul_f32_e32 v133, 0xbfb8aa3b, v53
	v_mul_f32_e32 v134, 0xbfb8aa3b, v54
	v_mul_f32_e32 v135, 0xbfb8aa3b, v55
	v_exp_f32_e32 v132, v132
	v_exp_f32_e32 v133, v133
	v_exp_f32_e32 v134, v134
	v_exp_f32_e32 v135, v135
	v_add_f32_e32 v132, 1.0, v132
	v_add_f32_e32 v133, 1.0, v133
	v_add_f32_e32 v134, 1.0, v134
	v_add_f32_e32 v135, 1.0, v135
	v_rcp_f32_e32 v132, v132
	v_rcp_f32_e32 v133, v133
	v_rcp_f32_e32 v134, v134
	v_rcp_f32_e32 v135, v135
	s_nop 0
	v_cvt_pk_bf16_f32 v136, v132, v133
	v_cvt_pk_bf16_f32 v137, v134, v135
	ds_write_b64 v155, v[136:137] offset:4352
	v_mul_f32_e32 v132, 0xbfb8aa3b, v48
	v_mul_f32_e32 v133, 0xbfb8aa3b, v49
	v_mul_f32_e32 v134, 0xbfb8aa3b, v50
	v_mul_f32_e32 v135, 0xbfb8aa3b, v51
	v_exp_f32_e32 v132, v132
	v_exp_f32_e32 v133, v133
	v_exp_f32_e32 v134, v134
	v_exp_f32_e32 v135, v135
	v_add_f32_e32 v132, 1.0, v132
	v_add_f32_e32 v133, 1.0, v133
	v_add_f32_e32 v134, 1.0, v134
	v_add_f32_e32 v135, 1.0, v135
	v_rcp_f32_e32 v132, v132
	v_rcp_f32_e32 v133, v133
	v_rcp_f32_e32 v134, v134
	v_rcp_f32_e32 v135, v135
	s_nop 0
	v_cvt_pk_bf16_f32 v138, v132, v133
	v_cvt_pk_bf16_f32 v139, v134, v135
	ds_write_b64 v155, v[138:139] offset:4384
	v_mul_f32_e32 v132, 0xbfb8aa3b, v44
	v_mul_f32_e32 v133, 0xbfb8aa3b, v45
	v_mul_f32_e32 v134, 0xbfb8aa3b, v46
	v_mul_f32_e32 v135, 0xbfb8aa3b, v47
	v_exp_f32_e32 v132, v132
	v_exp_f32_e32 v133, v133
	v_exp_f32_e32 v134, v134
	v_exp_f32_e32 v135, v135
	v_add_f32_e32 v132, 1.0, v132
	v_add_f32_e32 v133, 1.0, v133
	v_add_f32_e32 v134, 1.0, v134
	v_add_f32_e32 v135, 1.0, v135
	v_rcp_f32_e32 v132, v132
	v_rcp_f32_e32 v133, v133
	v_rcp_f32_e32 v134, v134
	v_rcp_f32_e32 v135, v135
	s_nop 0
	v_cvt_pk_bf16_f32 v136, v132, v133
	v_cvt_pk_bf16_f32 v137, v134, v135
	ds_write_b64 v155, v[136:137] offset:8704
	v_mul_f32_e32 v132, 0xbfb8aa3b, v40
	v_mul_f32_e32 v133, 0xbfb8aa3b, v41
	v_mul_f32_e32 v134, 0xbfb8aa3b, v42
	v_mul_f32_e32 v135, 0xbfb8aa3b, v43
	v_exp_f32_e32 v132, v132
	v_exp_f32_e32 v133, v133
	v_exp_f32_e32 v134, v134
	v_exp_f32_e32 v135, v135
	v_add_f32_e32 v132, 1.0, v132
	v_add_f32_e32 v133, 1.0, v133
	v_add_f32_e32 v134, 1.0, v134
	v_add_f32_e32 v135, 1.0, v135
	v_rcp_f32_e32 v132, v132
	v_rcp_f32_e32 v133, v133
	v_rcp_f32_e32 v134, v134
	v_rcp_f32_e32 v135, v135
	s_nop 0
	v_cvt_pk_bf16_f32 v138, v132, v133
	v_cvt_pk_bf16_f32 v139, v134, v135
	ds_write_b64 v155, v[138:139] offset:8736
	v_mul_f32_e32 v132, 0xbfb8aa3b, v36
	v_mul_f32_e32 v133, 0xbfb8aa3b, v37
	v_mul_f32_e32 v134, 0xbfb8aa3b, v38
	v_mul_f32_e32 v135, 0xbfb8aa3b, v39
	v_exp_f32_e32 v132, v132
	v_exp_f32_e32 v133, v133
	v_exp_f32_e32 v134, v134
	v_exp_f32_e32 v135, v135
	v_add_f32_e32 v132, 1.0, v132
	v_add_f32_e32 v133, 1.0, v133
	v_add_f32_e32 v134, 1.0, v134
	v_add_f32_e32 v135, 1.0, v135
	v_rcp_f32_e32 v132, v132
	v_rcp_f32_e32 v133, v133
	v_rcp_f32_e32 v134, v134
	v_rcp_f32_e32 v135, v135
	s_nop 0
	v_cvt_pk_bf16_f32 v136, v132, v133
	v_cvt_pk_bf16_f32 v137, v134, v135
	ds_write_b64 v155, v[136:137] offset:13056
	v_mul_f32_e32 v132, 0xbfb8aa3b, v32
	v_mul_f32_e32 v133, 0xbfb8aa3b, v33
	v_mul_f32_e32 v134, 0xbfb8aa3b, v34
	v_mul_f32_e32 v135, 0xbfb8aa3b, v35
	v_exp_f32_e32 v132, v132
	v_exp_f32_e32 v133, v133
	v_exp_f32_e32 v134, v134
	v_exp_f32_e32 v135, v135
	v_add_f32_e32 v132, 1.0, v132
	v_add_f32_e32 v133, 1.0, v133
	v_add_f32_e32 v134, 1.0, v134
	v_add_f32_e32 v135, 1.0, v135
	v_rcp_f32_e32 v132, v132
	v_rcp_f32_e32 v133, v133
	v_rcp_f32_e32 v134, v134
	v_rcp_f32_e32 v135, v135
	s_nop 0
	v_cvt_pk_bf16_f32 v138, v132, v133
	v_cvt_pk_bf16_f32 v139, v134, v135
	ds_write_b64 v155, v[138:139] offset:13088
	s_waitcnt lgkmcnt(0)
	s_barrier
	ds_read_b128 v[132:135], v156 offset:0
	ds_read_b128 v[136:139], v156 offset:8704
	s_add_u32 s8, s6, 0x80000
	s_addc_u32 s9, s7, 0
	s_waitcnt lgkmcnt(1)
	global_store_dwordx4 v157, v[132:135], s[8:9] sc1
	s_add_u32 s8, s6, 0xa0000
	s_addc_u32 s9, s7, 0
	s_waitcnt lgkmcnt(0)
	global_store_dwordx4 v157, v[136:139], s[8:9] sc1
	ds_read_b128 v[132:135], v156 offset:17408
	ds_read_b128 v[136:139], v156 offset:26112
	s_add_u32 s8, s6, 0xc0000
	s_addc_u32 s9, s7, 0
	s_waitcnt lgkmcnt(1)
	global_store_dwordx4 v157, v[132:135], s[8:9] sc1
	s_add_u32 s8, s6, 0xe0000
	s_addc_u32 s9, s7, 0
	s_waitcnt lgkmcnt(0)
	global_store_dwordx4 v157, v[136:139], s[8:9] sc1
	s_barrier
	v_mul_f32_e32 v132, 0xbfb8aa3b, v28
	v_mul_f32_e32 v133, 0xbfb8aa3b, v29
	v_mul_f32_e32 v134, 0xbfb8aa3b, v30
	v_mul_f32_e32 v135, 0xbfb8aa3b, v31
	v_exp_f32_e32 v132, v132
	v_exp_f32_e32 v133, v133
	v_exp_f32_e32 v134, v134
	v_exp_f32_e32 v135, v135
	v_add_f32_e32 v132, 1.0, v132
	v_add_f32_e32 v133, 1.0, v133
	v_add_f32_e32 v134, 1.0, v134
	v_add_f32_e32 v135, 1.0, v135
	v_rcp_f32_e32 v132, v132
	v_rcp_f32_e32 v133, v133
	v_rcp_f32_e32 v134, v134
	v_rcp_f32_e32 v135, v135
	s_nop 0
	v_cvt_pk_bf16_f32 v136, v132, v133
	v_cvt_pk_bf16_f32 v137, v134, v135
	ds_write_b64 v155, v[136:137] offset:0
	v_mul_f32_e32 v132, 0xbfb8aa3b, v24
	v_mul_f32_e32 v133, 0xbfb8aa3b, v25
	v_mul_f32_e32 v134, 0xbfb8aa3b, v26
	v_mul_f32_e32 v135, 0xbfb8aa3b, v27
	v_exp_f32_e32 v132, v132
	v_exp_f32_e32 v133, v133
	v_exp_f32_e32 v134, v134
	v_exp_f32_e32 v135, v135
	v_add_f32_e32 v132, 1.0, v132
	v_add_f32_e32 v133, 1.0, v133
	v_add_f32_e32 v134, 1.0, v134
	v_add_f32_e32 v135, 1.0, v135
	v_rcp_f32_e32 v132, v132
	v_rcp_f32_e32 v133, v133
	v_rcp_f32_e32 v134, v134
	v_rcp_f32_e32 v135, v135
	s_nop 0
	v_cvt_pk_bf16_f32 v138, v132, v133
	v_cvt_pk_bf16_f32 v139, v134, v135
	ds_write_b64 v155, v[138:139] offset:32
	v_mul_f32_e32 v132, 0xbfb8aa3b, v20
	v_mul_f32_e32 v133, 0xbfb8aa3b, v21
	v_mul_f32_e32 v134, 0xbfb8aa3b, v22
	v_mul_f32_e32 v135, 0xbfb8aa3b, v23
	v_exp_f32_e32 v132, v132
	v_exp_f32_e32 v133, v133
	v_exp_f32_e32 v134, v134
	v_exp_f32_e32 v135, v135
	v_add_f32_e32 v132, 1.0, v132
	v_add_f32_e32 v133, 1.0, v133
	v_add_f32_e32 v134, 1.0, v134
	v_add_f32_e32 v135, 1.0, v135
	v_rcp_f32_e32 v132, v132
	v_rcp_f32_e32 v133, v133
	v_rcp_f32_e32 v134, v134
	v_rcp_f32_e32 v135, v135
	s_nop 0
	v_cvt_pk_bf16_f32 v136, v132, v133
	v_cvt_pk_bf16_f32 v137, v134, v135
	ds_write_b64 v155, v[136:137] offset:4352
	v_mul_f32_e32 v132, 0xbfb8aa3b, v16
	v_mul_f32_e32 v133, 0xbfb8aa3b, v17
	v_mul_f32_e32 v134, 0xbfb8aa3b, v18
	v_mul_f32_e32 v135, 0xbfb8aa3b, v19
	v_exp_f32_e32 v132, v132
	v_exp_f32_e32 v133, v133
	v_exp_f32_e32 v134, v134
	v_exp_f32_e32 v135, v135
	v_add_f32_e32 v132, 1.0, v132
	v_add_f32_e32 v133, 1.0, v133
	v_add_f32_e32 v134, 1.0, v134
	v_add_f32_e32 v135, 1.0, v135
	v_rcp_f32_e32 v132, v132
	v_rcp_f32_e32 v133, v133
	v_rcp_f32_e32 v134, v134
	v_rcp_f32_e32 v135, v135
	s_nop 0
	v_cvt_pk_bf16_f32 v138, v132, v133
	v_cvt_pk_bf16_f32 v139, v134, v135
	ds_write_b64 v155, v[138:139] offset:4384
	v_mul_f32_e32 v132, 0xbfb8aa3b, v12
	v_mul_f32_e32 v133, 0xbfb8aa3b, v13
	v_mul_f32_e32 v134, 0xbfb8aa3b, v14
	v_mul_f32_e32 v135, 0xbfb8aa3b, v15
	v_exp_f32_e32 v132, v132
	v_exp_f32_e32 v133, v133
	v_exp_f32_e32 v134, v134
	v_exp_f32_e32 v135, v135
	v_add_f32_e32 v132, 1.0, v132
	v_add_f32_e32 v133, 1.0, v133
	v_add_f32_e32 v134, 1.0, v134
	v_add_f32_e32 v135, 1.0, v135
	v_rcp_f32_e32 v132, v132
	v_rcp_f32_e32 v133, v133
	v_rcp_f32_e32 v134, v134
	v_rcp_f32_e32 v135, v135
	s_nop 0
	v_cvt_pk_bf16_f32 v136, v132, v133
	v_cvt_pk_bf16_f32 v137, v134, v135
	ds_write_b64 v155, v[136:137] offset:8704
	v_mul_f32_e32 v132, 0xbfb8aa3b, v8
	v_mul_f32_e32 v133, 0xbfb8aa3b, v9
	v_mul_f32_e32 v134, 0xbfb8aa3b, v10
	v_mul_f32_e32 v135, 0xbfb8aa3b, v11
	v_exp_f32_e32 v132, v132
	v_exp_f32_e32 v133, v133
	v_exp_f32_e32 v134, v134
	v_exp_f32_e32 v135, v135
	v_add_f32_e32 v132, 1.0, v132
	v_add_f32_e32 v133, 1.0, v133
	v_add_f32_e32 v134, 1.0, v134
	v_add_f32_e32 v135, 1.0, v135
	v_rcp_f32_e32 v132, v132
	v_rcp_f32_e32 v133, v133
	v_rcp_f32_e32 v134, v134
	v_rcp_f32_e32 v135, v135
	s_nop 0
	v_cvt_pk_bf16_f32 v138, v132, v133
	v_cvt_pk_bf16_f32 v139, v134, v135
	ds_write_b64 v155, v[138:139] offset:8736
	v_mul_f32_e32 v132, 0xbfb8aa3b, v4
	v_mul_f32_e32 v133, 0xbfb8aa3b, v5
	v_mul_f32_e32 v134, 0xbfb8aa3b, v6
	v_mul_f32_e32 v135, 0xbfb8aa3b, v7
	v_exp_f32_e32 v132, v132
	v_exp_f32_e32 v133, v133
	v_exp_f32_e32 v134, v134
	v_exp_f32_e32 v135, v135
	v_add_f32_e32 v132, 1.0, v132
	v_add_f32_e32 v133, 1.0, v133
	v_add_f32_e32 v134, 1.0, v134
	v_add_f32_e32 v135, 1.0, v135
	v_rcp_f32_e32 v132, v132
	v_rcp_f32_e32 v133, v133
	v_rcp_f32_e32 v134, v134
	v_rcp_f32_e32 v135, v135
	s_nop 0
	v_cvt_pk_bf16_f32 v136, v132, v133
	v_cvt_pk_bf16_f32 v137, v134, v135
	ds_write_b64 v155, v[136:137] offset:13056
	v_mul_f32_e32 v132, 0xbfb8aa3b, v0
	v_mul_f32_e32 v133, 0xbfb8aa3b, v1
	v_mul_f32_e32 v134, 0xbfb8aa3b, v2
	v_mul_f32_e32 v135, 0xbfb8aa3b, v3
	v_exp_f32_e32 v132, v132
	v_exp_f32_e32 v133, v133
	v_exp_f32_e32 v134, v134
	v_exp_f32_e32 v135, v135
	v_add_f32_e32 v132, 1.0, v132
	v_add_f32_e32 v133, 1.0, v133
	v_add_f32_e32 v134, 1.0, v134
	v_add_f32_e32 v135, 1.0, v135
	v_rcp_f32_e32 v132, v132
	v_rcp_f32_e32 v133, v133
	v_rcp_f32_e32 v134, v134
	v_rcp_f32_e32 v135, v135
	s_nop 0
	v_cvt_pk_bf16_f32 v138, v132, v133
	v_cvt_pk_bf16_f32 v139, v134, v135
	ds_write_b64 v155, v[138:139] offset:13088
	s_waitcnt lgkmcnt(0)
	s_barrier
	ds_read_b128 v[132:135], v156 offset:0
	ds_read_b128 v[136:139], v156 offset:8704
	s_add_u32 s8, s6, 0x80100
	s_addc_u32 s9, s7, 0
	s_waitcnt lgkmcnt(1)
	global_store_dwordx4 v157, v[132:135], s[8:9] sc1
	s_add_u32 s8, s6, 0xa0100
	s_addc_u32 s9, s7, 0
	s_waitcnt lgkmcnt(0)
	global_store_dwordx4 v157, v[136:139], s[8:9] sc1
	ds_read_b128 v[132:135], v156 offset:17408
	ds_read_b128 v[136:139], v156 offset:26112
	s_add_u32 s8, s6, 0xc0100
	s_addc_u32 s9, s7, 0
	s_waitcnt lgkmcnt(1)
	global_store_dwordx4 v157, v[132:135], s[8:9] sc1
	s_add_u32 s8, s6, 0xe0100
	s_addc_u32 s9, s7, 0
	s_waitcnt lgkmcnt(0)
	global_store_dwordx4 v157, v[136:139], s[8:9] sc1
	s_barrier
	s_branch .LBB0_93
.Lipe_old:
	v_mov_b32_e32 v161, v148
	s_movk_i32 s0, 0x2020
	v_bfe_u32 v158, v161, 6, 2
	v_lshl_or_b32 v155, v158, 5, s96
	s_cmpk_gt_u32 s96, 0xbff
	v_cmp_gt_i32_e64 s[16:17], s0, v155
	s_movk_i32 s0, 0x7ff
	s_cselect_b64 s[12:13], -1, 0
	s_cmpk_gt_u32 s96, 0xfff
	v_cmp_lt_i32_e64 s[14:15], s0, v155
	s_cselect_b64 s[0:1], -1, 0
	s_cmpk_gt_u32 s96, 0x13ff
	s_cselect_b64 s[6:7], -1, 0
	v_writelane_b32 v255, s6, 34
	s_cmpk_gt_u32 s96, 0x17ff
	v_and_b32_e32 v157, 15, v161
	v_writelane_b32 v255, s7, 35
	s_cselect_b64 s[6:7], -1, 0
	v_writelane_b32 v255, s6, 36
	s_cmpk_lt_u32 s96, 0x2000
	v_ashrrev_i32_e32 v128, 2, v161
	v_writelane_b32 v255, s7, 37
	s_cselect_b64 s[6:7], -1, 0
	v_writelane_b32 v255, s6, 38
	s_cmpk_gt_u32 s96, 0x1fff
	v_and_b32_e32 v160, 0xffffffc0, v128
	v_or_b32_e32 v128, s4, v157
	v_writelane_b32 v255, s7, 39
	s_cselect_b64 s[6:7], -1, 0
	s_cmpk_gt_u32 s96, 0xdff
	v_add_u32_e32 v132, v128, v160
	s_cselect_b64 s[70:71], -1, 0
	v_mov_b32_e32 v128, 0x3db504f3
	v_writelane_b32 v255, s6, 40
	v_cndmask_b32_e64 v130, v128, 1.0, s[70:71]
	v_and_b32_e32 v128, 64, v161
	v_writelane_b32 v255, s7, 41
	v_cmp_eq_u32_e64 s[6:7], 0, v128
	v_bfe_u32 v159, v161, 4, 2
	s_movk_i32 s5, 0x3ff
	v_writelane_b32 v255, s6, 42
	v_lshlrev_b32_e32 v156, 2, v159
	v_mov_b32_e32 v131, v130
	v_cmp_lt_i32_e64 s[10:11], s5, v155
	v_writelane_b32 v255, s7, 43
	v_mov_b32_e32 v136, 0
	s_and_saveexec_b64 s[18:19], s[16:17]
	s_cbranch_execz .LBB0_149
	v_cmp_gt_i32_e64 s[8:9], s51, v132
	s_and_saveexec_b64 s[6:7], s[14:15]
	s_xor_b64 s[6:7], exec, s[6:7]
	s_cbranch_execz .LBB0_140
	s_andn2_b64 vcc, exec, s[12:13]
	s_cbranch_vccnz .LBB0_140
	s_mov_b64 s[20:21], -1
	s_and_b64 vcc, exec, s[0:1]
	s_cbranch_vccz .LBB0_135
	v_readlane_b32 s20, v255, 34
	v_readlane_b32 s21, v255, 35
	s_andn2_b64 vcc, exec, s[20:21]
	v_mov_b32_e32 v135, v127
	v_mov_b32_e32 v134, v126
	v_mov_b32_e32 v137, v125
	v_mov_b32_e32 v136, v124
	v_mov_b32_e32 v139, v123
	v_mov_b32_e32 v138, v122
	v_mov_b32_e32 v141, v121
	v_mov_b32_e32 v140, v120
	s_cbranch_vccnz .LBB0_134
	v_readlane_b32 s22, v255, 36
	v_readlane_b32 s23, v255, 37
	s_mov_b64 s[20:21], -1
	s_and_b64 vcc, exec, s[22:23]
	s_cbranch_vccz .LBB0_130
	v_readlane_b32 s22, v255, 40
	v_readlane_b32 s23, v255, 41
	s_and_b64 vcc, exec, s[22:23]
	s_cbranch_vccz .LBB0_125
	v_ashrrev_i32_e32 v133, 31, v132
	v_readlane_b32 s20, v255, 23
	v_lshlrev_b64 v[134:135], 7, v[132:133]
	v_readlane_b32 s21, v255, 24
	v_lshlrev_b32_e32 v128, 2, v156
	s_nop 0
	v_lshl_add_u64 v[134:135], s[20:21], 0, v[134:135]
	v_lshl_add_u64 v[134:135], v[134:135], 0, v[128:129]
	global_store_dwordx4 v[134:135], v[124:127], off sc1
	global_store_dwordx4 v[134:135], v[120:123], off offset:64 sc1
	s_mov_b64 s[20:21], 0

.LBB0_1067:
	s_waitcnt vmcnt(0) lgkmcnt(0)
	s_barrier
	s_mov_b64 s[0:1], exec
	v_readlane_b32 s4, v255, 19
	v_readlane_b32 s5, v255, 20
	s_and_b64 s[4:5], s[0:1], s[4:5]
	s_mov_b64 exec, s[4:5]
	s_cbranch_execz .LBB0_1073
	s_mov_b64 s[6:7], exec
	v_mbcnt_lo_u32_b32 v0, s6, 0
	v_mbcnt_hi_u32_b32 v0, s7, v0
	v_cmp_eq_u32_e32 vcc, 0, v0
	buffer_wbl2 sc1
	s_waitcnt vmcnt(0)
	buffer_inv sc1
	s_and_saveexec_b64 s[4:5], vcc
	s_cbranch_execz .LBB0_1070
	s_bcnt1_i32_b64 s3, s[6:7]
	v_mov_b32_e32 v0, 0
	v_mov_b32_e32 v1, s3
	global_atomic_add v0, v1, s[78:79]

.LBB0_1071:
	s_sleep 16
	global_load_dword v1, v0, s[78:79] sc1
	s_waitcnt vmcnt(0)
	v_cmp_gt_u32_e32 vcc, s3, v1
	s_cbranch_vccnz .LBB0_1071
.LBB0_1072:
	buffer_inv sc1
.LBB0_1073:
	s_or_b64 exec, exec, s[0:1]
	v_mov_b32_e32 v3, 0
	v_mov_b32_e32 v2, v148
	s_mov_b64 s[0:1], 0
	v_mov_b32_e32 v0, 0
	v_mov_b32_e32 v1, v3
	s_barrier

.LBB0_1122:
	v_readlane_b32 s92, v255, 19
	v_readlane_b32 s93, v255, 20
	s_waitcnt vmcnt(0)
	s_barrier
	s_and_saveexec_b64 s[4:5], s[92:93]
	s_cbranch_execz .LBB0_1128
	s_mov_b64 s[8:9], exec
	v_mbcnt_lo_u32_b32 v0, s8, 0
	v_mbcnt_hi_u32_b32 v0, s9, v0
	v_cmp_eq_u32_e32 vcc, 0, v0
	buffer_wbl2 sc1
	s_waitcnt vmcnt(0)
	buffer_inv sc1
	s_and_saveexec_b64 s[6:7], vcc
	s_cbranch_execz .LBB0_1125
	s_bcnt1_i32_b64 s3, s[8:9]
	v_mov_b32_e32 v0, 0
	v_mov_b32_e32 v1, s3
	global_atomic_add v0, v1, s[78:79]

.LBB0_1126:
	s_sleep 16
	global_load_dword v1, v0, s[78:79] sc1
	s_waitcnt vmcnt(0)
	v_cmp_gt_u32_e32 vcc, s3, v1
	s_cbranch_vccnz .LBB0_1126
.LBB0_1127:
	buffer_inv sc1
.LBB0_1128:
	s_or_b64 exec, exec, s[4:5]
	v_mov_b32_e32 v2, v148
	s_cmpk_gt_i32 s2, 0x41f
	s_barrier
	s_cbranch_scc1 .LBB0_1135
	v_ashrrev_i32_e32 v3, 31, v2
	v_lshlrev_b64 v[0:1], 2, v[2:3]
	v_lshl_add_u64 v[4:5], s[80:81], 0, v[0:1]
	v_add_co_u32_e32 v8, vcc, 0x8000, v4
	v_lshl_add_u64 v[0:1], s[82:83], 0, v[0:1]
	s_nop 0
	v_addc_co_u32_e32 v9, vcc, 0, v5, vcc
	v_add_co_u32_e32 v12, vcc, 0x1000, v4
	v_readlane_b32 s4, v255, 23
	s_nop 0
	v_addc_co_u32_e32 v13, vcc, 0, v5, vcc
	v_add_co_u32_e32 v14, vcc, 0x9000, v4
	v_readlane_b32 s5, v255, 24
	s_nop 0
	v_addc_co_u32_e32 v15, vcc, 0, v5, vcc
	v_add_co_u32_e32 v22, vcc, 0x2000, v4
	global_load_dword v6, v[4:5], off
	global_load_dword v7, v[8:9], off
	s_nop 0
	global_load_dword v8, v[8:9], off offset:2048
	s_nop 0
	global_load_dword v9, v[12:13], off
	global_load_dword v10, v[14:15], off
	global_load_dword v11, v[14:15], off offset:2048
	s_nop 0
	global_load_dword v12, v[12:13], off offset:2048
	s_nop 0
	global_load_dword v13, v[4:5], off offset:2048
	v_addc_co_u32_e32 v23, vcc, 0, v5, vcc
	v_add_co_u32_e32 v16, vcc, 0xa000, v4
	v_lshlrev_b32_e32 v40, 4, v2
	s_nop 0
	v_addc_co_u32_e32 v17, vcc, 0, v5, vcc
	v_add_co_u32_e32 v20, vcc, 0x3000, v4
	s_lshl_b32 s3, s2, 6
	s_nop 0
	v_addc_co_u32_e32 v21, vcc, 0, v5, vcc
	v_add_co_u32_e32 v24, vcc, 0xb000, v4
	s_lshl_b32 s12, s50, 6
	s_nop 0
	v_addc_co_u32_e32 v25, vcc, 0, v5, vcc
	v_add_co_u32_e32 v30, vcc, 0x4000, v4
	global_load_dword v14, v[22:23], off
	global_load_dword v15, v[16:17], off
	s_nop 0
	global_load_dword v16, v[16:17], off offset:2048
	s_nop 0
	global_load_dword v17, v[20:21], off
	global_load_dword v18, v[24:25], off
	global_load_dword v19, v[24:25], off offset:2048
	s_nop 0
	global_load_dword v20, v[20:21], off offset:2048
	s_nop 0
	global_load_dword v21, v[22:23], off offset:2048
	v_addc_co_u32_e32 v31, vcc, 0, v5, vcc
	v_add_co_u32_e32 v24, vcc, 0xc000, v4
	s_mov_b32 s13, 0xbfb8aa3b
	s_nop 0
	v_addc_co_u32_e32 v25, vcc, 0, v5, vcc
	v_add_co_u32_e32 v28, vcc, 0x5000, v4
	s_mov_b32 s14, 0x800000
	s_nop 0
	v_addc_co_u32_e32 v29, vcc, 0, v5, vcc
	v_add_co_u32_e32 v32, vcc, 0xd000, v4
	s_mov_b32 s15, 0x3f317217
	s_nop 0
	v_addc_co_u32_e32 v33, vcc, 0, v5, vcc
	v_add_co_u32_e32 v38, vcc, 0x6000, v4
	global_load_dword v22, v[30:31], off
	global_load_dword v23, v[24:25], off
	s_nop 0
	global_load_dword v24, v[24:25], off offset:2048
	s_nop 0
	global_load_dword v25, v[28:29], off
	global_load_dword v26, v[32:33], off
	global_load_dword v27, v[32:33], off offset:2048
	s_nop 0
	global_load_dword v28, v[28:29], off offset:2048
	s_nop 0
	global_load_dword v29, v[30:31], off offset:2048
	v_addc_co_u32_e32 v39, vcc, 0, v5, vcc
	v_add_co_u32_e32 v32, vcc, 0xe000, v4
	s_mov_b32 s16, 0x7f800000
	s_nop 0
	v_addc_co_u32_e32 v33, vcc, 0, v5, vcc
	v_add_co_u32_e32 v36, vcc, 0x7000, v4
	v_mov_b32_e32 v41, 0x41b17218
	s_nop 0
	v_addc_co_u32_e32 v37, vcc, 0, v5, vcc
	v_add_co_u32_e32 v4, vcc, 0xf000, v4
	s_mov_b32 s17, 0x3db8aa3b
	s_nop 0
	v_addc_co_u32_e32 v5, vcc, 0, v5, vcc
	global_load_dword v30, v[38:39], off
	global_load_dword v31, v[32:33], off
	s_nop 0
	global_load_dword v32, v[32:33], off offset:2048
	s_nop 0
	global_load_dword v33, v[36:37], off
	global_load_dword v34, v[4:5], off
	global_load_dword v35, v[4:5], off offset:2048
	s_nop 0
	global_load_dword v36, v[36:37], off offset:2048
	s_nop 0
	global_load_dword v37, v[38:39], off offset:2048
	s_nop 0
	global_load_dword v38, v[0:1], off
	global_load_dword v39, v[0:1], off offset:2048
	v_lshlrev_b32_e32 v0, 2, v2
	v_ashrrev_i32_e32 v1, 31, v0
	v_lshlrev_b64 v[4:5], 1, v[2:3]
	v_lshl_add_u64 v[0:1], v[0:1], 2, s[4:5]
	v_lshl_add_u64 v[2:3], s[62:63], 0, v[4:5]
	v_lshl_add_u64 v[4:5], s[54:55], 0, v[4:5]
	s_mov_b64 s[4:5], 0x10600000
	v_lshl_add_u64 v[4:5], v[4:5], 0, s[4:5]
	s_mov_b32 s10, s2

.LBB0_1135:
	s_waitcnt vmcnt(0)
	s_barrier
	s_and_saveexec_b64 s[4:5], s[92:93]
	s_cbranch_execz .LBB0_1141
	s_mov_b64 s[8:9], exec
	v_mbcnt_lo_u32_b32 v0, s8, 0
	v_mbcnt_hi_u32_b32 v0, s9, v0
	v_cmp_eq_u32_e32 vcc, 0, v0
	buffer_wbl2 sc1
	s_waitcnt vmcnt(0)
	buffer_inv sc1
	s_and_saveexec_b64 s[6:7], vcc
	s_cbranch_execz .LBB0_1138
	s_bcnt1_i32_b64 s3, s[8:9]
	v_mov_b32_e32 v0, 0
	v_mov_b32_e32 v1, s3
	global_atomic_add v0, v1, s[78:79]

.LBB0_1139:
	s_sleep 16
	global_load_dword v1, v0, s[78:79] sc1
	s_waitcnt vmcnt(0)
	v_cmp_gt_u32_e32 vcc, s3, v1
	s_cbranch_vccnz .LBB0_1139
.LBB0_1140:
	buffer_inv sc1
.LBB0_1141:
	s_or_b64 exec, exec, s[4:5]
	s_cmpk_gt_u32 s50, 0xbf
	s_cselect_b64 s[46:47], -1, 0
	s_and_b64 s[4:5], s[46:47], exec
	s_cselect_b32 s3, 0x80, s50
	s_cmp_ge_i32 s2, s3
	s_cselect_b64 s[4:5], -1, 0
	s_cmpk_gt_i32 s2, 0x7f
	s_cselect_b64 s[6:7], -1, 0
	s_or_b64 s[4:5], s[4:5], s[6:7]
	s_and_b64 vcc, exec, s[4:5]
	s_barrier
	s_cbranch_vccnz .LBB0_1174
	s_movk_i32 s33, 0x4200
	s_movk_i32 s51, 0x70
	s_mov_b32 s49, 0
	v_mov_b32_e32 v1, 0
	s_movk_i32 s84, 0xf0
	v_mov_b32_e32 v137, 0x16000
	s_mov_b32 s85, s2
	s_branch .LBB0_1144

.LBB0_1207:
	s_waitcnt vmcnt(0)
	s_barrier
	s_and_saveexec_b64 s[4:5], s[92:93]
	v_readlane_b32 s36, v255, 27
	v_readlane_b32 s37, v255, 28
	s_cbranch_execz .LBB0_1213
	s_mov_b64 s[8:9], exec
	v_mbcnt_lo_u32_b32 v0, s8, 0
	v_mbcnt_hi_u32_b32 v0, s9, v0
	v_cmp_eq_u32_e32 vcc, 0, v0
	buffer_wbl2 sc1
	s_waitcnt vmcnt(0)
	buffer_inv sc1
	s_and_saveexec_b64 s[6:7], vcc
	s_cbranch_execz .LBB0_1210
	s_bcnt1_i32_b64 s3, s[8:9]
	v_mov_b32_e32 v0, 0
	v_mov_b32_e32 v1, s3
	global_atomic_add v0, v1, s[36:37]

.LBB0_1211:
	s_sleep 16
	global_load_dword v1, v0, s[36:37] sc1
	s_waitcnt vmcnt(0)
	v_cmp_gt_u32_e32 vcc, s3, v1
	s_cbranch_vccnz .LBB0_1211
.LBB0_1212:
	buffer_inv sc1
.LBB0_1213:
	s_or_b64 exec, exec, s[4:5]
	v_readlane_b32 s6, v255, 17
	v_readlane_b32 s7, v255, 18
	s_andn2_b64 vcc, exec, s[6:7]
	s_nop 0
	v_cndmask_b32_e64 v0, 0, 1, s[6:7]
	v_cmp_ne_u32_e64 s[4:5], 1, v0
	s_barrier
	s_cbranch_vccnz .LBB0_1219
	v_mbcnt_lo_u32_b32 v0, -1, 0
	s_add_u32 s8, s54, 0x14800000
	v_mbcnt_hi_u32_b32 v38, -1, v0
	s_addc_u32 s9, s55, 0
	s_lshl_b32 s3, s2, 8
	s_brev_b32 s10, 31
	v_and_b32_e32 v0, 64, v38
	s_add_i32 s20, s3, -16
	s_lshl_b32 s21, s50, 8
	s_movk_i32 s22, 0x100
	v_mov_b32_e32 v25, 0
	s_mov_b32 s11, -1
	s_mov_b64 s[12:13], 0x18a00000
	s_mov_b32 s23, 0x18a00000
	v_mov_b32_e32 v27, 0x358637bd
	s_mov_b32 s24, 0x800000
	s_mov_b64 s[14:15], 0x8000
	v_add_u32_e32 v39, 64, v0
	v_xor_b32_e32 v40, 8, v38
	v_xor_b32_e32 v41, 4, v38
	v_xor_b32_e32 v42, 2, v38
	v_xor_b32_e32 v43, 1, v38
	s_mov_b32 s25, s2
	s_branch .LBB0_1216

.LBB0_1219:
	s_waitcnt vmcnt(0)
	s_waitcnt vmcnt(0)
	s_barrier
	s_and_saveexec_b64 s[6:7], s[92:93]
	s_cbranch_execz .LBB0_1225
	s_mov_b64 s[10:11], exec
	v_mbcnt_lo_u32_b32 v0, s10, 0
	v_mbcnt_hi_u32_b32 v0, s11, v0
	v_cmp_eq_u32_e32 vcc, 0, v0
	buffer_wbl2 sc1
	s_waitcnt vmcnt(0)
	buffer_inv sc1
	s_and_saveexec_b64 s[8:9], vcc
	s_cbranch_execz .LBB0_1222
	s_bcnt1_i32_b64 s3, s[10:11]
	v_mov_b32_e32 v0, 0
	v_mov_b32_e32 v1, s3
	global_atomic_add v0, v1, s[36:37]

.LBB0_1223:
	s_sleep 16
	global_load_dword v1, v0, s[36:37] sc1
	s_waitcnt vmcnt(0)
	v_cmp_gt_u32_e32 vcc, s3, v1
	s_cbranch_vccnz .LBB0_1223
.LBB0_1224:
	buffer_inv sc1
.LBB0_1225:
	s_or_b64 exec, exec, s[6:7]
	s_cmpk_lt_i32 s2, 0x400
	s_cselect_b64 s[8:9], -1, 0
	s_cmpk_gt_i32 s2, 0x3ff
	s_barrier
	s_cbranch_scc1 .LBB0_1234
	s_add_u32 s3, s54, 0x1280000
	s_addc_u32 s20, s55, 0
	s_add_u32 s21, s54, 0x35200080
	s_addc_u32 s22, s55, 0
	s_mov_b32 s23, 0x1ffff0
	s_waitcnt vmcnt(1)
	v_mov_b32_e32 v129, 0
	s_movk_i32 s24, 0x3000
	s_mov_b64 s[6:7], 0x80
	s_movk_i32 s25, 0x100
	s_movk_i32 s26, 0x110
	s_mov_b32 s27, s2
	s_mov_b32 s28, s2
	s_branch .LBB0_1228

.LBB0_1234:
	s_waitcnt vmcnt(0)
	s_barrier
	s_and_saveexec_b64 s[6:7], s[92:93]
	s_cbranch_execz .LBB0_1240
	s_mov_b64 s[12:13], exec
	v_mbcnt_lo_u32_b32 v0, s12, 0
	v_mbcnt_hi_u32_b32 v0, s13, v0
	v_cmp_eq_u32_e32 vcc, 0, v0
	buffer_wbl2 sc1
	s_waitcnt vmcnt(0)
	buffer_inv sc1
	s_and_saveexec_b64 s[10:11], vcc
	s_cbranch_execz .LBB0_1237
	s_bcnt1_i32_b64 s3, s[12:13]
	v_mov_b32_e32 v0, 0
	v_mov_b32_e32 v1, s3
	global_atomic_add v0, v1, s[36:37]

.LBB0_1238:
	s_sleep 16
	global_load_dword v1, v0, s[36:37] sc1
	s_waitcnt vmcnt(0)
	v_cmp_gt_u32_e32 vcc, s3, v1
	s_cbranch_vccnz .LBB0_1238
.LBB0_1239:
	buffer_inv sc1
.LBB0_1240:
	s_or_b64 exec, exec, s[6:7]
	v_cndmask_b32_e64 v0, 0, 1, s[8:9]
	v_cmp_ne_u32_e64 s[6:7], 1, v0
	s_andn2_b64 vcc, exec, s[8:9]
	s_barrier
	s_cbranch_vccnz .LBB0_1249
	s_add_u32 s3, s54, 0x1480000
	s_addc_u32 s20, s55, 0
	s_mov_b32 s21, 0x1ffff0
	s_waitcnt vmcnt(1)
	v_mov_b32_e32 v129, 0
	s_movk_i32 s22, 0x3000
	s_mov_b64 s[8:9], 0x80
	s_movk_i32 s23, 0x100
	s_mov_b32 s24, 0xfffffc0
	s_movk_i32 s25, 0xc0
	s_movk_i32 s26, 0x110
	s_mov_b32 s27, s2
	s_waitcnt vmcnt(0)
	s_branch .LBB0_1243

.LBB0_1249:
	s_waitcnt vmcnt(0)
	s_barrier
	s_and_saveexec_b64 s[8:9], s[92:93]
	s_cbranch_execz .LBB0_1255
	s_mov_b64 s[12:13], exec
	v_mbcnt_lo_u32_b32 v0, s12, 0
	v_mbcnt_hi_u32_b32 v0, s13, v0
	v_cmp_eq_u32_e32 vcc, 0, v0
	buffer_wbl2 sc1
	s_waitcnt vmcnt(0)
	buffer_inv sc1
	s_and_saveexec_b64 s[10:11], vcc
	s_cbranch_execz .LBB0_1252
	s_bcnt1_i32_b64 s3, s[12:13]
	v_mov_b32_e32 v0, 0
	v_mov_b32_e32 v1, s3
	global_atomic_add v0, v1, s[36:37]

.LBB0_1253:
	s_sleep 16
	global_load_dword v1, v0, s[36:37] sc1
	s_waitcnt vmcnt(0)
	v_cmp_gt_u32_e32 vcc, s3, v1
	s_cbranch_vccnz .LBB0_1253
.LBB0_1254:
	buffer_inv sc1
.LBB0_1255:
	s_or_b64 exec, exec, s[8:9]
	s_and_b64 vcc, exec, s[4:5]
	s_barrier
	s_cbranch_vccnz .LBB0_1266
	s_add_u32 s8, s74, 0x2000
	s_addc_u32 s9, s75, 0
	s_add_u32 s10, s74, 0x3000
	v_mbcnt_lo_u32_b32 v0, -1, 0
	s_addc_u32 s11, s75, 0
	v_mbcnt_hi_u32_b32 v123, -1, v0
	s_add_u32 s12, s74, 0x4000
	s_mov_b32 s16, 0x358637bd
	v_and_b32_e32 v0, 64, v123
	v_add_u32_e32 v122, 0x2000, v150
	s_addc_u32 s13, s75, 0
	s_lshl_b32 s3, s2, 8
	s_lshl_b32 s15, s50, 8
	s_movk_i32 s24, 0x200
	v_mov_b32_e32 v65, 0
	s_mov_b32 s14, 0x3a800000
	v_mov_b64_e32 v[66:67], s[16:17]
	s_mov_b32 s25, 0x800000
	v_add_u32_e32 v124, 64, v0
	v_xor_b32_e32 v125, 32, v123
	v_xor_b32_e32 v126, 16, v123
	v_xor_b32_e32 v127, 8, v123
	s_waitcnt vmcnt(1)
	v_xor_b32_e32 v128, 4, v123
	v_xor_b32_e32 v129, 2, v123
	v_xor_b32_e32 v130, 1, v123
	s_mov_b32 s26, s2

.LBB0_1270:
	s_sleep 16
	global_load_dword v1, v0, s[36:37] sc1
	s_waitcnt vmcnt(0)
	v_cmp_gt_u32_e32 vcc, s3, v1
	s_cbranch_vccnz .LBB0_1270
.LBB0_1271:
	buffer_inv sc1
.LBB0_1272:
	s_or_b64 exec, exec, s[8:9]
	s_andn2_b64 vcc, exec, s[0:1]
	s_barrier
	s_cbranch_vccnz .LBB0_1281
	s_add_u32 s3, s54, 0x1680000
	s_addc_u32 s18, s55, 0
	s_add_u32 s19, s54, 0x4000080
	s_addc_u32 s20, s55, 0
	s_mov_b32 s21, 0x1ffff0
	s_waitcnt vmcnt(1)
	v_mov_b32_e32 v129, 0
	s_movk_i32 s22, 0x3000
	s_mov_b64 s[0:1], 0x80
	s_movk_i32 s23, 0x100
	s_mov_b32 s24, 0xfffffc0
	s_movk_i32 s25, 0xc0
	s_movk_i32 s26, 0x110
	s_mov_b32 s27, s2
	s_mov_b32 s28, s2
	s_waitcnt vmcnt(0)
	s_branch .LBB0_1275

.LBB0_1281:
	s_waitcnt vmcnt(0)
	s_barrier
	s_and_saveexec_b64 s[0:1], s[92:93]
	s_cbranch_execz .LBB0_1287
	s_mov_b64 s[10:11], exec
	v_mbcnt_lo_u32_b32 v0, s10, 0
	v_mbcnt_hi_u32_b32 v0, s11, v0
	v_cmp_eq_u32_e32 vcc, 0, v0
	buffer_wbl2 sc1
	s_waitcnt vmcnt(0)
	buffer_inv sc1
	s_and_saveexec_b64 s[8:9], vcc
	s_cbranch_execz .LBB0_1284
	s_bcnt1_i32_b64 s3, s[10:11]
	v_mov_b32_e32 v0, 0
	v_mov_b32_e32 v1, s3
	global_atomic_add v0, v1, s[36:37]

.LBB0_1285:
	s_sleep 16
	global_load_dword v1, v0, s[36:37] sc1
	s_waitcnt vmcnt(0)
	v_cmp_gt_u32_e32 vcc, s3, v1
	s_cbranch_vccnz .LBB0_1285
.LBB0_1286:
	buffer_inv sc1
.LBB0_1287:
	s_or_b64 exec, exec, s[0:1]
	s_and_b64 vcc, exec, s[6:7]
	s_barrier
	s_cbranch_vccnz .LBB0_1296
	s_add_u32 s3, s54, 0x1e80000
	s_addc_u32 s16, s55, 0
	s_mov_b32 s17, 0x7fff0
	s_waitcnt vmcnt(1)
	v_mov_b32_e32 v129, 0
	s_movk_i32 s18, 0x3000
	s_mov_b64 s[0:1], 0x80
	s_movk_i32 s19, 0x100
	s_mov_b32 s20, 0xfffffc0
	s_movk_i32 s21, 0xc0
	s_movk_i32 s22, 0x110
	s_mov_b32 s23, s2
	s_waitcnt vmcnt(0)
	s_branch .LBB0_1290

.LBB0_1296:
	s_waitcnt vmcnt(0)
	s_barrier
	s_and_saveexec_b64 s[0:1], s[92:93]
	s_cbranch_execz .LBB0_1302
	s_mov_b64 s[8:9], exec
	v_mbcnt_lo_u32_b32 v0, s8, 0
	v_mbcnt_hi_u32_b32 v0, s9, v0
	v_cmp_eq_u32_e32 vcc, 0, v0
	buffer_wbl2 sc1
	s_waitcnt vmcnt(0)
	buffer_inv sc1
	s_and_saveexec_b64 s[6:7], vcc
	s_cbranch_execz .LBB0_1299
	s_bcnt1_i32_b64 s3, s[8:9]
	v_mov_b32_e32 v0, 0
	v_mov_b32_e32 v1, s3
	global_atomic_add v0, v1, s[36:37]

.LBB0_1300:
	s_sleep 16
	global_load_dword v1, v0, s[36:37] sc1
	s_waitcnt vmcnt(0)
	v_cmp_gt_u32_e32 vcc, s3, v1
	s_cbranch_vccnz .LBB0_1300
.LBB0_1301:
	buffer_inv sc1
.LBB0_1302:
	s_or_b64 exec, exec, s[0:1]
	s_and_b64 vcc, exec, s[4:5]
	s_barrier
	s_cbranch_vccnz .LBB0_1309
	v_mbcnt_lo_u32_b32 v0, -1, 0
	v_mbcnt_hi_u32_b32 v25, -1, v0
	s_add_u32 s0, s74, 0x5000
	v_and_b32_e32 v0, 64, v25
	s_addc_u32 s1, s75, 0
	s_lshl_b32 s3, s2, 8
	s_lshl_b32 s10, s50, 8
	v_mov_b32_e32 v17, 0
	v_mov_b32_e32 v24, 0x358637bd
	s_mov_b32 s11, 0x800000
	v_add_u32_e32 v26, 64, v0
	v_xor_b32_e32 v27, 32, v25
	v_xor_b32_e32 v28, 16, v25
	v_xor_b32_e32 v29, 8, v25
	v_xor_b32_e32 v30, 4, v25
	v_xor_b32_e32 v31, 2, v25
	v_xor_b32_e32 v32, 1, v25
